# code placement: every run of >=8 MFMAs starts at 0 mod 8 bytes (one s_nop 0 in front of the runs that straddled)
# baseline (speedup 1.0000x reference)
.LBB0_181:
	ds_read_b128 v[128:131], v173
	ds_read_b128 v[132:135], v173 offset:1024
	ds_read_b128 v[136:139], v173 offset:2048
	ds_read_b128 v[140:143], v173 offset:3072
	ds_read_b128 v[162:165], v174
	ds_read_b128 v[166:169], v174 offset:1024
	ds_read_b128 v[176:179], v174 offset:2048
	ds_read_b128 v[180:183], v174 offset:3072
	s_add_u32 s6, s4, 0xfff80080
	s_addc_u32 s7, s5, -1
	s_cmp_eq_u32 s96, 28
	s_cselect_b32 s9, s26, s7
	s_cselect_b32 s8, s27, s6
	s_cselect_b32 s7, s86, s95
	s_cselect_b32 s6, s91, s94
	v_lshl_add_u64 v[216:217], s[4:5], 0, v[158:159]
	s_add_i32 m0, s47, 0xc000
	ds_read_b128 v[184:187], v175
	ds_read_b128 v[188:191], v175 offset:1024
	ds_read_b128 v[192:195], v175 offset:2048
	ds_read_b128 v[196:199], v175 offset:3072
	ds_read_b128 v[200:203], v175 offset:4096
	ds_read_b128 v[204:207], v175 offset:5120
	ds_read_b128 v[208:211], v175 offset:6144
	ds_read_b128 v[212:215], v175 offset:7168
	global_load_lds_dwordx4 v[216:217], off
	v_lshl_add_u64 v[216:217], s[4:5], 0, v[160:161]
	s_add_i32 m0, s47, 0xe000
	s_nop 0
	global_load_lds_dwordx4 v[216:217], off
	s_waitcnt vmcnt(8)
	s_waitcnt lgkmcnt(0)
	s_barrier
	s_setprio 1
	s_waitcnt lgkmcnt(0)
	s_nop 0
	v_mfma_f32_16x16x32_bf16 v[124:127], v[128:131], v[184:187], v[124:127]
	v_mfma_f32_16x16x32_bf16 v[120:123], v[136:139], v[184:187], v[120:123]
	v_mfma_f32_16x16x32_bf16 v[108:111], v[128:131], v[192:195], v[108:111]
	v_mfma_f32_16x16x32_bf16 v[104:107], v[136:139], v[192:195], v[104:107]
	v_mfma_f32_16x16x32_bf16 v[92:95], v[128:131], v[200:203], v[92:95]
	v_mfma_f32_16x16x32_bf16 v[88:91], v[136:139], v[200:203], v[88:91]
	v_mfma_f32_16x16x32_bf16 v[76:79], v[128:131], v[208:211], v[76:79]
	v_mfma_f32_16x16x32_bf16 v[72:75], v[136:139], v[208:211], v[72:75]
	v_mfma_f32_16x16x32_bf16 v[124:127], v[132:135], v[188:191], v[124:127]
	v_mfma_f32_16x16x32_bf16 v[120:123], v[140:143], v[188:191], v[120:123]
	v_mfma_f32_16x16x32_bf16 v[108:111], v[132:135], v[196:199], v[108:111]
	v_mfma_f32_16x16x32_bf16 v[104:107], v[140:143], v[196:199], v[104:107]
	v_mfma_f32_16x16x32_bf16 v[92:95], v[132:135], v[204:207], v[92:95]
	v_mfma_f32_16x16x32_bf16 v[88:91], v[140:143], v[204:207], v[88:91]
	v_mfma_f32_16x16x32_bf16 v[76:79], v[132:135], v[212:215], v[76:79]
	v_mfma_f32_16x16x32_bf16 v[72:75], v[140:143], v[212:215], v[72:75]
	s_setprio 0
	s_setprio 1
	v_mfma_f32_16x16x32_bf16 v[116:119], v[162:165], v[184:187], v[116:119]
	v_mfma_f32_16x16x32_bf16 v[112:115], v[176:179], v[184:187], v[112:115]
	v_mfma_f32_16x16x32_bf16 v[100:103], v[162:165], v[192:195], v[100:103]
	v_mfma_f32_16x16x32_bf16 v[96:99], v[176:179], v[192:195], v[96:99]
	v_mfma_f32_16x16x32_bf16 v[84:87], v[162:165], v[200:203], v[84:87]
	v_mfma_f32_16x16x32_bf16 v[80:83], v[176:179], v[200:203], v[80:83]
	v_mfma_f32_16x16x32_bf16 v[68:71], v[162:165], v[208:211], v[68:71]
	v_mfma_f32_16x16x32_bf16 v[64:67], v[176:179], v[208:211], v[64:67]
	v_mfma_f32_16x16x32_bf16 v[116:119], v[166:169], v[188:191], v[116:119]
	v_mfma_f32_16x16x32_bf16 v[112:115], v[180:183], v[188:191], v[112:115]
	v_mfma_f32_16x16x32_bf16 v[100:103], v[166:169], v[196:199], v[100:103]
	v_mfma_f32_16x16x32_bf16 v[96:99], v[180:183], v[196:199], v[96:99]
	v_mfma_f32_16x16x32_bf16 v[84:87], v[166:169], v[204:207], v[84:87]
	v_mfma_f32_16x16x32_bf16 v[80:83], v[180:183], v[204:207], v[80:83]
	v_mfma_f32_16x16x32_bf16 v[68:71], v[166:169], v[212:215], v[68:71]
	v_mfma_f32_16x16x32_bf16 v[64:67], v[180:183], v[212:215], v[64:67]
	s_setprio 0
	s_barrier
	s_add_i32 s97, s30, s44
	v_lshl_add_u64 v[216:217], s[6:7], 0, v[146:147]
	s_mov_b32 m0, s97
	ds_read_b128 v[184:187], v175 offset:16384
	ds_read_b128 v[188:191], v175 offset:17408
	ds_read_b128 v[192:195], v175 offset:18432
	ds_read_b128 v[196:199], v175 offset:19456
	ds_read_b128 v[200:203], v175 offset:20480
	ds_read_b128 v[204:207], v175 offset:21504
	ds_read_b128 v[208:211], v175 offset:22528
	ds_read_b128 v[212:215], v175 offset:23552
	global_load_lds_dwordx4 v[216:217], off
	s_add_i32 m0, s97, 0x2000
	s_add_u32 vcc_lo, s6, 0x80000
	v_lshl_add_u64 v[218:219], s[6:7], 0, v[144:145]
	s_addc_u32 vcc_hi, s7, 0
	s_add_i32 s97, s31, s44
	global_load_lds_dwordx4 v[218:219], off
	v_lshl_add_u64 v[220:221], vcc, 0, v[146:147]
	s_mov_b32 m0, s97
	v_lshl_add_u64 v[222:223], s[8:9], 0, v[144:145]
	global_load_lds_dwordx4 v[220:221], off
	v_lshl_add_u64 v[220:221], vcc, 0, v[144:145]
	s_add_i32 m0, s97, 0x2000
	s_nop 0
	global_load_lds_dwordx4 v[220:221], off
	v_lshl_add_u64 v[220:221], s[8:9], 0, v[146:147]
	s_mov_b32 m0, s47
	s_nop 0
	global_load_lds_dwordx4 v[220:221], off
	s_mov_b32 m0, s48
	s_nop 0
	global_load_lds_dwordx4 v[222:223], off
	s_waitcnt vmcnt(8)
	s_waitcnt lgkmcnt(0)
	s_barrier
	s_setprio 1
	s_waitcnt lgkmcnt(0)
	s_nop 0
	v_mfma_f32_16x16x32_bf16 v[60:63], v[128:131], v[184:187], v[60:63]
	v_mfma_f32_16x16x32_bf16 v[56:59], v[136:139], v[184:187], v[56:59]
	v_mfma_f32_16x16x32_bf16 v[44:47], v[128:131], v[192:195], v[44:47]
	v_mfma_f32_16x16x32_bf16 v[40:43], v[136:139], v[192:195], v[40:43]
	v_mfma_f32_16x16x32_bf16 v[28:31], v[128:131], v[200:203], v[28:31]
	v_mfma_f32_16x16x32_bf16 v[24:27], v[136:139], v[200:203], v[24:27]
	v_mfma_f32_16x16x32_bf16 v[12:15], v[128:131], v[208:211], v[12:15]
	v_mfma_f32_16x16x32_bf16 v[8:11], v[136:139], v[208:211], v[8:11]
	v_mfma_f32_16x16x32_bf16 v[60:63], v[132:135], v[188:191], v[60:63]
	v_mfma_f32_16x16x32_bf16 v[56:59], v[140:143], v[188:191], v[56:59]
	v_mfma_f32_16x16x32_bf16 v[44:47], v[132:135], v[196:199], v[44:47]
	v_mfma_f32_16x16x32_bf16 v[40:43], v[140:143], v[196:199], v[40:43]
	v_mfma_f32_16x16x32_bf16 v[28:31], v[132:135], v[204:207], v[28:31]
	v_mfma_f32_16x16x32_bf16 v[24:27], v[140:143], v[204:207], v[24:27]
	v_mfma_f32_16x16x32_bf16 v[12:15], v[132:135], v[212:215], v[12:15]
	v_mfma_f32_16x16x32_bf16 v[8:11], v[140:143], v[212:215], v[8:11]
	s_setprio 0
	s_setprio 1
	v_mfma_f32_16x16x32_bf16 v[52:55], v[162:165], v[184:187], v[52:55]
	v_mfma_f32_16x16x32_bf16 v[48:51], v[176:179], v[184:187], v[48:51]
	v_mfma_f32_16x16x32_bf16 v[36:39], v[162:165], v[192:195], v[36:39]
	v_mfma_f32_16x16x32_bf16 v[32:35], v[176:179], v[192:195], v[32:35]
	v_mfma_f32_16x16x32_bf16 v[20:23], v[162:165], v[200:203], v[20:23]
	v_mfma_f32_16x16x32_bf16 v[16:19], v[176:179], v[200:203], v[16:19]
	v_mfma_f32_16x16x32_bf16 v[4:7], v[162:165], v[208:211], v[4:7]
	v_mfma_f32_16x16x32_bf16 v[0:3], v[176:179], v[208:211], v[0:3]
	v_mfma_f32_16x16x32_bf16 v[52:55], v[166:169], v[188:191], v[52:55]
	v_mfma_f32_16x16x32_bf16 v[48:51], v[180:183], v[188:191], v[48:51]
	v_mfma_f32_16x16x32_bf16 v[36:39], v[166:169], v[196:199], v[36:39]
	v_mfma_f32_16x16x32_bf16 v[32:35], v[180:183], v[196:199], v[32:35]
	v_mfma_f32_16x16x32_bf16 v[20:23], v[166:169], v[204:207], v[20:23]
	v_mfma_f32_16x16x32_bf16 v[16:19], v[180:183], v[204:207], v[16:19]
	v_mfma_f32_16x16x32_bf16 v[4:7], v[166:169], v[212:215], v[4:7]
	v_mfma_f32_16x16x32_bf16 v[0:3], v[180:183], v[212:215], v[0:3]
	s_setprio 0
	s_barrier
	s_add_i32 s97, 0, 0x18000
	s_add_i32 vcc_lo, 0, 0x1c000
	v_add_u32_e32 v140, s97, v153
	v_add_u32_e32 v180, vcc_lo, v153
	ds_read_b128 v[128:131], v140
	ds_read_b128 v[132:135], v140 offset:1024
	ds_read_b128 v[136:139], v140 offset:2048
	ds_read_b128 v[140:143], v140 offset:3072
	ds_read_b128 v[162:165], v180
	ds_read_b128 v[166:169], v180 offset:1024
	ds_read_b128 v[176:179], v180 offset:2048
	ds_read_b128 v[180:183], v180 offset:3072
	s_add_u32 s8, s8, 0x80000
	s_addc_u32 s9, s9, 0
	s_mov_b32 m0, s49
	v_lshl_add_u64 v[224:225], s[8:9], 0, v[146:147]
	ds_read_b128 v[184:187], v175 offset:32768
	ds_read_b128 v[188:191], v175 offset:33792
	ds_read_b128 v[192:195], v175 offset:34816
	ds_read_b128 v[196:199], v175 offset:35840
	ds_read_b128 v[200:203], v175 offset:36864
	ds_read_b128 v[204:207], v175 offset:37888
	ds_read_b128 v[208:211], v175 offset:38912
	ds_read_b128 v[212:215], v175 offset:39936
	global_load_lds_dwordx4 v[224:225], off
	v_lshl_add_u64 v[224:225], s[8:9], 0, v[144:145]
	s_mov_b32 m0, s50
	s_nop 0
	global_load_lds_dwordx4 v[224:225], off
	s_waitcnt vmcnt(8)
	s_waitcnt lgkmcnt(0)
	s_barrier
	s_setprio 1
	s_waitcnt lgkmcnt(0)
	s_nop 0
	v_mfma_f32_16x16x32_bf16 v[124:127], v[128:131], v[184:187], v[124:127]
	v_mfma_f32_16x16x32_bf16 v[120:123], v[136:139], v[184:187], v[120:123]
	v_mfma_f32_16x16x32_bf16 v[108:111], v[128:131], v[192:195], v[108:111]
	v_mfma_f32_16x16x32_bf16 v[104:107], v[136:139], v[192:195], v[104:107]
	v_mfma_f32_16x16x32_bf16 v[92:95], v[128:131], v[200:203], v[92:95]
	v_mfma_f32_16x16x32_bf16 v[88:91], v[136:139], v[200:203], v[88:91]
	v_mfma_f32_16x16x32_bf16 v[76:79], v[128:131], v[208:211], v[76:79]
	v_mfma_f32_16x16x32_bf16 v[72:75], v[136:139], v[208:211], v[72:75]
	v_mfma_f32_16x16x32_bf16 v[124:127], v[132:135], v[188:191], v[124:127]
	v_mfma_f32_16x16x32_bf16 v[120:123], v[140:143], v[188:191], v[120:123]
	v_mfma_f32_16x16x32_bf16 v[108:111], v[132:135], v[196:199], v[108:111]
	v_mfma_f32_16x16x32_bf16 v[104:107], v[140:143], v[196:199], v[104:107]
	v_mfma_f32_16x16x32_bf16 v[92:95], v[132:135], v[204:207], v[92:95]
	v_mfma_f32_16x16x32_bf16 v[88:91], v[140:143], v[204:207], v[88:91]
	v_mfma_f32_16x16x32_bf16 v[76:79], v[132:135], v[212:215], v[76:79]
	v_mfma_f32_16x16x32_bf16 v[72:75], v[140:143], v[212:215], v[72:75]
	s_setprio 0
	s_setprio 1
	v_mfma_f32_16x16x32_bf16 v[116:119], v[162:165], v[184:187], v[116:119]
	v_mfma_f32_16x16x32_bf16 v[112:115], v[176:179], v[184:187], v[112:115]
	v_mfma_f32_16x16x32_bf16 v[100:103], v[162:165], v[192:195], v[100:103]
	v_mfma_f32_16x16x32_bf16 v[96:99], v[176:179], v[192:195], v[96:99]
	v_mfma_f32_16x16x32_bf16 v[84:87], v[162:165], v[200:203], v[84:87]
	v_mfma_f32_16x16x32_bf16 v[80:83], v[176:179], v[200:203], v[80:83]
	v_mfma_f32_16x16x32_bf16 v[68:71], v[162:165], v[208:211], v[68:71]
	v_mfma_f32_16x16x32_bf16 v[64:67], v[176:179], v[208:211], v[64:67]
	v_mfma_f32_16x16x32_bf16 v[116:119], v[166:169], v[188:191], v[116:119]
	v_mfma_f32_16x16x32_bf16 v[112:115], v[180:183], v[188:191], v[112:115]
	v_mfma_f32_16x16x32_bf16 v[100:103], v[166:169], v[196:199], v[100:103]
	v_mfma_f32_16x16x32_bf16 v[96:99], v[180:183], v[196:199], v[96:99]
	v_mfma_f32_16x16x32_bf16 v[84:87], v[166:169], v[204:207], v[84:87]
	v_mfma_f32_16x16x32_bf16 v[80:83], v[180:183], v[204:207], v[80:83]
	v_mfma_f32_16x16x32_bf16 v[68:71], v[166:169], v[212:215], v[68:71]
	v_mfma_f32_16x16x32_bf16 v[64:67], v[180:183], v[212:215], v[64:67]
	s_setprio 0
	s_barrier
	s_add_i32 s8, s97, s44
	v_lshl_add_u64 v[216:217], v[216:217], 0, s[78:79]
	s_mov_b32 m0, s8
	ds_read_b128 v[184:187], v175 offset:49152
	ds_read_b128 v[188:191], v175 offset:50176
	ds_read_b128 v[192:195], v175 offset:51200
	ds_read_b128 v[196:199], v175 offset:52224
	ds_read_b128 v[200:203], v175 offset:53248
	ds_read_b128 v[204:207], v175 offset:54272
	ds_read_b128 v[208:211], v175 offset:55296
	ds_read_b128 v[212:215], v175 offset:56320
	global_load_lds_dwordx4 v[216:217], off
	s_add_i32 m0, s8, 0x2000
	s_add_u32 s6, s6, 0x80080
	v_lshl_add_u64 v[216:217], v[218:219], 0, s[78:79]
	s_addc_u32 s7, s7, 0
	s_add_i32 s8, vcc_lo, s44
	global_load_lds_dwordx4 v[216:217], off
	v_lshl_add_u64 v[216:217], s[6:7], 0, v[146:147]
	s_mov_b32 m0, s8
	s_nop 0
	global_load_lds_dwordx4 v[216:217], off
	v_lshl_add_u64 v[216:217], s[6:7], 0, v[144:145]
	s_add_i32 m0, s8, 0x2000
	s_nop 0
	global_load_lds_dwordx4 v[216:217], off
	v_lshl_add_u64 v[216:217], v[220:221], 0, s[78:79]
	s_mov_b32 m0, s71
	s_nop 0
	global_load_lds_dwordx4 v[216:217], off
	v_lshl_add_u64 v[216:217], v[222:223], 0, s[78:79]
	s_mov_b32 m0, s84
	s_nop 0
	global_load_lds_dwordx4 v[216:217], off
	s_waitcnt vmcnt(8)
	s_waitcnt lgkmcnt(0)
	s_barrier
	s_setprio 1
	s_waitcnt lgkmcnt(0)
	v_mfma_f32_16x16x32_bf16 v[60:63], v[128:131], v[184:187], v[60:63]
	v_mfma_f32_16x16x32_bf16 v[56:59], v[136:139], v[184:187], v[56:59]
	v_mfma_f32_16x16x32_bf16 v[44:47], v[128:131], v[192:195], v[44:47]
	v_mfma_f32_16x16x32_bf16 v[40:43], v[136:139], v[192:195], v[40:43]
	v_mfma_f32_16x16x32_bf16 v[28:31], v[128:131], v[200:203], v[28:31]
	v_mfma_f32_16x16x32_bf16 v[24:27], v[136:139], v[200:203], v[24:27]
	v_mfma_f32_16x16x32_bf16 v[12:15], v[128:131], v[208:211], v[12:15]
	v_mfma_f32_16x16x32_bf16 v[8:11], v[136:139], v[208:211], v[8:11]
	v_mfma_f32_16x16x32_bf16 v[60:63], v[132:135], v[188:191], v[60:63]
	v_mfma_f32_16x16x32_bf16 v[56:59], v[140:143], v[188:191], v[56:59]
	v_mfma_f32_16x16x32_bf16 v[44:47], v[132:135], v[196:199], v[44:47]
	v_mfma_f32_16x16x32_bf16 v[40:43], v[140:143], v[196:199], v[40:43]
	v_mfma_f32_16x16x32_bf16 v[28:31], v[132:135], v[204:207], v[28:31]
	v_mfma_f32_16x16x32_bf16 v[24:27], v[140:143], v[204:207], v[24:27]
	v_mfma_f32_16x16x32_bf16 v[12:15], v[132:135], v[212:215], v[12:15]
	v_mfma_f32_16x16x32_bf16 v[8:11], v[140:143], v[212:215], v[8:11]
	s_setprio 0
	s_setprio 1
	v_mfma_f32_16x16x32_bf16 v[52:55], v[162:165], v[184:187], v[52:55]
	v_mfma_f32_16x16x32_bf16 v[48:51], v[176:179], v[184:187], v[48:51]
	v_mfma_f32_16x16x32_bf16 v[36:39], v[162:165], v[192:195], v[36:39]
	v_mfma_f32_16x16x32_bf16 v[32:35], v[176:179], v[192:195], v[32:35]
	v_mfma_f32_16x16x32_bf16 v[20:23], v[162:165], v[200:203], v[20:23]
	v_mfma_f32_16x16x32_bf16 v[16:19], v[176:179], v[200:203], v[16:19]
	v_mfma_f32_16x16x32_bf16 v[4:7], v[162:165], v[208:211], v[4:7]
	v_mfma_f32_16x16x32_bf16 v[0:3], v[176:179], v[208:211], v[0:3]
	v_mfma_f32_16x16x32_bf16 v[52:55], v[166:169], v[188:191], v[52:55]
	v_mfma_f32_16x16x32_bf16 v[48:51], v[180:183], v[188:191], v[48:51]
	v_mfma_f32_16x16x32_bf16 v[36:39], v[166:169], v[196:199], v[36:39]
	v_mfma_f32_16x16x32_bf16 v[32:35], v[180:183], v[196:199], v[32:35]
	v_mfma_f32_16x16x32_bf16 v[20:23], v[166:169], v[204:207], v[20:23]
	v_mfma_f32_16x16x32_bf16 v[16:19], v[180:183], v[204:207], v[16:19]
	v_mfma_f32_16x16x32_bf16 v[4:7], v[166:169], v[212:215], v[4:7]
	v_mfma_f32_16x16x32_bf16 v[0:3], v[180:183], v[212:215], v[0:3]
	s_setprio 0
	s_barrier
	s_add_i32 s96, s96, 2
	s_add_u32 s4, s4, 0x100
	s_addc_u32 s5, s5, 0
	s_add_u32 s94, s94, 0x100
	s_addc_u32 s95, s95, 0
	s_cmp_gt_u32 s96, 29
	s_cbranch_scc0 .LBB0_181
	s_and_b64 vcc, exec, s[88:89]
	s_cbranch_vccz .LBB0_184
	s_barrier

.LBB0_468:
	ds_read_b128 v[128:131], v173
	ds_read_b128 v[132:135], v173 offset:1024
	ds_read_b128 v[136:139], v173 offset:2048
	ds_read_b128 v[140:143], v173 offset:3072
	ds_read_b128 v[162:165], v174
	ds_read_b128 v[166:169], v174 offset:1024
	ds_read_b128 v[176:179], v174 offset:2048
	ds_read_b128 v[180:183], v174 offset:3072
	s_add_u32 s6, s4, 0xfff80080
	s_addc_u32 s7, s5, -1
	s_cmp_eq_u32 s85, 28
	s_cselect_b32 s9, s26, s7
	s_cselect_b32 s8, s27, s6
	s_cselect_b32 s7, s35, s84
	s_cselect_b32 s6, s68, s77
	v_lshl_add_u64 v[216:217], s[4:5], 0, v[158:159]
	s_add_i32 m0, s44, 0xc000
	ds_read_b128 v[184:187], v175
	ds_read_b128 v[188:191], v175 offset:1024
	ds_read_b128 v[192:195], v175 offset:2048
	ds_read_b128 v[196:199], v175 offset:3072
	ds_read_b128 v[200:203], v175 offset:4096
	ds_read_b128 v[204:207], v175 offset:5120
	ds_read_b128 v[208:211], v175 offset:6144
	ds_read_b128 v[212:215], v175 offset:7168
	global_load_lds_dwordx4 v[216:217], off
	v_lshl_add_u64 v[216:217], s[4:5], 0, v[160:161]
	s_add_i32 m0, s44, 0xe000
	s_nop 0
	global_load_lds_dwordx4 v[216:217], off
	s_waitcnt vmcnt(8)
	s_waitcnt lgkmcnt(0)
	s_barrier
	s_setprio 1
	s_waitcnt lgkmcnt(0)
	v_mfma_f32_16x16x32_bf16 v[124:127], v[128:131], v[184:187], v[124:127]
	v_mfma_f32_16x16x32_bf16 v[120:123], v[136:139], v[184:187], v[120:123]
	v_mfma_f32_16x16x32_bf16 v[108:111], v[128:131], v[192:195], v[108:111]
	v_mfma_f32_16x16x32_bf16 v[104:107], v[136:139], v[192:195], v[104:107]
	v_mfma_f32_16x16x32_bf16 v[92:95], v[128:131], v[200:203], v[92:95]
	v_mfma_f32_16x16x32_bf16 v[88:91], v[136:139], v[200:203], v[88:91]
	v_mfma_f32_16x16x32_bf16 v[76:79], v[128:131], v[208:211], v[76:79]
	v_mfma_f32_16x16x32_bf16 v[72:75], v[136:139], v[208:211], v[72:75]
	v_mfma_f32_16x16x32_bf16 v[124:127], v[132:135], v[188:191], v[124:127]
	v_mfma_f32_16x16x32_bf16 v[120:123], v[140:143], v[188:191], v[120:123]
	v_mfma_f32_16x16x32_bf16 v[108:111], v[132:135], v[196:199], v[108:111]
	v_mfma_f32_16x16x32_bf16 v[104:107], v[140:143], v[196:199], v[104:107]
	v_mfma_f32_16x16x32_bf16 v[92:95], v[132:135], v[204:207], v[92:95]
	v_mfma_f32_16x16x32_bf16 v[88:91], v[140:143], v[204:207], v[88:91]
	v_mfma_f32_16x16x32_bf16 v[76:79], v[132:135], v[212:215], v[76:79]
	v_mfma_f32_16x16x32_bf16 v[72:75], v[140:143], v[212:215], v[72:75]
	s_setprio 0
	s_setprio 1
	v_mfma_f32_16x16x32_bf16 v[116:119], v[162:165], v[184:187], v[116:119]
	v_mfma_f32_16x16x32_bf16 v[112:115], v[176:179], v[184:187], v[112:115]
	v_mfma_f32_16x16x32_bf16 v[100:103], v[162:165], v[192:195], v[100:103]
	v_mfma_f32_16x16x32_bf16 v[96:99], v[176:179], v[192:195], v[96:99]
	v_mfma_f32_16x16x32_bf16 v[84:87], v[162:165], v[200:203], v[84:87]
	v_mfma_f32_16x16x32_bf16 v[80:83], v[176:179], v[200:203], v[80:83]
	v_mfma_f32_16x16x32_bf16 v[68:71], v[162:165], v[208:211], v[68:71]
	v_mfma_f32_16x16x32_bf16 v[64:67], v[176:179], v[208:211], v[64:67]
	v_mfma_f32_16x16x32_bf16 v[116:119], v[166:169], v[188:191], v[116:119]
	v_mfma_f32_16x16x32_bf16 v[112:115], v[180:183], v[188:191], v[112:115]
	v_mfma_f32_16x16x32_bf16 v[100:103], v[166:169], v[196:199], v[100:103]
	v_mfma_f32_16x16x32_bf16 v[96:99], v[180:183], v[196:199], v[96:99]
	v_mfma_f32_16x16x32_bf16 v[84:87], v[166:169], v[204:207], v[84:87]
	v_mfma_f32_16x16x32_bf16 v[80:83], v[180:183], v[204:207], v[80:83]
	v_mfma_f32_16x16x32_bf16 v[68:71], v[166:169], v[212:215], v[68:71]
	v_mfma_f32_16x16x32_bf16 v[64:67], v[180:183], v[212:215], v[64:67]
	s_setprio 0
	s_barrier
	s_add_i32 s89, s51, s43
	v_lshl_add_u64 v[216:217], s[6:7], 0, v[144:145]
	s_mov_b32 m0, s89
	ds_read_b128 v[184:187], v175 offset:16384
	ds_read_b128 v[188:191], v175 offset:17408
	ds_read_b128 v[192:195], v175 offset:18432
	ds_read_b128 v[196:199], v175 offset:19456
	ds_read_b128 v[200:203], v175 offset:20480
	ds_read_b128 v[204:207], v175 offset:21504
	ds_read_b128 v[208:211], v175 offset:22528
	ds_read_b128 v[212:215], v175 offset:23552
	global_load_lds_dwordx4 v[216:217], off
	s_add_i32 m0, s89, 0x2000
	s_add_u32 s90, s6, 0x80000
	v_lshl_add_u64 v[218:219], s[6:7], 0, v[146:147]
	s_addc_u32 s91, s7, 0
	s_add_i32 s89, s65, s43
	global_load_lds_dwordx4 v[218:219], off
	v_lshl_add_u64 v[220:221], s[90:91], 0, v[144:145]
	s_mov_b32 m0, s89
	v_lshl_add_u64 v[222:223], s[8:9], 0, v[146:147]
	global_load_lds_dwordx4 v[220:221], off
	v_lshl_add_u64 v[220:221], s[90:91], 0, v[146:147]
	s_add_i32 m0, s89, 0x2000
	s_nop 0
	global_load_lds_dwordx4 v[220:221], off
	v_lshl_add_u64 v[220:221], s[8:9], 0, v[144:145]
	s_mov_b32 m0, s44
	s_nop 0
	global_load_lds_dwordx4 v[220:221], off
	s_mov_b32 m0, s45
	s_nop 0
	global_load_lds_dwordx4 v[222:223], off
	s_waitcnt vmcnt(8)
	s_waitcnt lgkmcnt(0)
	s_barrier
	s_setprio 1
	s_waitcnt lgkmcnt(0)
	s_nop 0
	v_mfma_f32_16x16x32_bf16 v[60:63], v[128:131], v[184:187], v[60:63]
	v_mfma_f32_16x16x32_bf16 v[56:59], v[136:139], v[184:187], v[56:59]
	v_mfma_f32_16x16x32_bf16 v[44:47], v[128:131], v[192:195], v[44:47]
	v_mfma_f32_16x16x32_bf16 v[40:43], v[136:139], v[192:195], v[40:43]
	v_mfma_f32_16x16x32_bf16 v[28:31], v[128:131], v[200:203], v[28:31]
	v_mfma_f32_16x16x32_bf16 v[24:27], v[136:139], v[200:203], v[24:27]
	v_mfma_f32_16x16x32_bf16 v[12:15], v[128:131], v[208:211], v[12:15]
	v_mfma_f32_16x16x32_bf16 v[8:11], v[136:139], v[208:211], v[8:11]
	v_mfma_f32_16x16x32_bf16 v[60:63], v[132:135], v[188:191], v[60:63]
	v_mfma_f32_16x16x32_bf16 v[56:59], v[140:143], v[188:191], v[56:59]
	v_mfma_f32_16x16x32_bf16 v[44:47], v[132:135], v[196:199], v[44:47]
	v_mfma_f32_16x16x32_bf16 v[40:43], v[140:143], v[196:199], v[40:43]
	v_mfma_f32_16x16x32_bf16 v[28:31], v[132:135], v[204:207], v[28:31]
	v_mfma_f32_16x16x32_bf16 v[24:27], v[140:143], v[204:207], v[24:27]
	v_mfma_f32_16x16x32_bf16 v[12:15], v[132:135], v[212:215], v[12:15]
	v_mfma_f32_16x16x32_bf16 v[8:11], v[140:143], v[212:215], v[8:11]
	s_setprio 0
	s_setprio 1
	v_mfma_f32_16x16x32_bf16 v[52:55], v[162:165], v[184:187], v[52:55]
	v_mfma_f32_16x16x32_bf16 v[48:51], v[176:179], v[184:187], v[48:51]
	v_mfma_f32_16x16x32_bf16 v[36:39], v[162:165], v[192:195], v[36:39]
	v_mfma_f32_16x16x32_bf16 v[32:35], v[176:179], v[192:195], v[32:35]
	v_mfma_f32_16x16x32_bf16 v[20:23], v[162:165], v[200:203], v[20:23]
	v_mfma_f32_16x16x32_bf16 v[16:19], v[176:179], v[200:203], v[16:19]
	v_mfma_f32_16x16x32_bf16 v[4:7], v[162:165], v[208:211], v[4:7]
	v_mfma_f32_16x16x32_bf16 v[0:3], v[176:179], v[208:211], v[0:3]
	v_mfma_f32_16x16x32_bf16 v[52:55], v[166:169], v[188:191], v[52:55]
	v_mfma_f32_16x16x32_bf16 v[48:51], v[180:183], v[188:191], v[48:51]
	v_mfma_f32_16x16x32_bf16 v[36:39], v[166:169], v[196:199], v[36:39]
	v_mfma_f32_16x16x32_bf16 v[32:35], v[180:183], v[196:199], v[32:35]
	v_mfma_f32_16x16x32_bf16 v[20:23], v[166:169], v[204:207], v[20:23]
	v_mfma_f32_16x16x32_bf16 v[16:19], v[180:183], v[204:207], v[16:19]
	v_mfma_f32_16x16x32_bf16 v[4:7], v[166:169], v[212:215], v[4:7]
	v_mfma_f32_16x16x32_bf16 v[0:3], v[180:183], v[212:215], v[0:3]
	s_setprio 0
	s_barrier
	s_add_i32 s89, 0, 0x18000
	s_add_i32 s90, 0, 0x1c000
	v_add_u32_e32 v140, s89, v153
	v_add_u32_e32 v180, s90, v153
	ds_read_b128 v[128:131], v140
	ds_read_b128 v[132:135], v140 offset:1024
	ds_read_b128 v[136:139], v140 offset:2048
	ds_read_b128 v[140:143], v140 offset:3072
	ds_read_b128 v[162:165], v180
	ds_read_b128 v[166:169], v180 offset:1024
	ds_read_b128 v[176:179], v180 offset:2048
	ds_read_b128 v[180:183], v180 offset:3072
	s_add_u32 s8, s8, 0x80000
	s_addc_u32 s9, s9, 0
	s_mov_b32 m0, s46
	v_lshl_add_u64 v[224:225], s[8:9], 0, v[144:145]
	ds_read_b128 v[184:187], v175 offset:32768
	ds_read_b128 v[188:191], v175 offset:33792
	ds_read_b128 v[192:195], v175 offset:34816
	ds_read_b128 v[196:199], v175 offset:35840
	ds_read_b128 v[200:203], v175 offset:36864
	ds_read_b128 v[204:207], v175 offset:37888
	ds_read_b128 v[208:211], v175 offset:38912
	ds_read_b128 v[212:215], v175 offset:39936
	global_load_lds_dwordx4 v[224:225], off
	v_lshl_add_u64 v[224:225], s[8:9], 0, v[146:147]
	s_mov_b32 m0, s47
	s_nop 0
	global_load_lds_dwordx4 v[224:225], off
	s_waitcnt vmcnt(8)
	s_waitcnt lgkmcnt(0)
	s_barrier
	s_setprio 1
	s_waitcnt lgkmcnt(0)
	s_nop 0
	v_mfma_f32_16x16x32_bf16 v[124:127], v[128:131], v[184:187], v[124:127]
	v_mfma_f32_16x16x32_bf16 v[120:123], v[136:139], v[184:187], v[120:123]
	v_mfma_f32_16x16x32_bf16 v[108:111], v[128:131], v[192:195], v[108:111]
	v_mfma_f32_16x16x32_bf16 v[104:107], v[136:139], v[192:195], v[104:107]
	v_mfma_f32_16x16x32_bf16 v[92:95], v[128:131], v[200:203], v[92:95]
	v_mfma_f32_16x16x32_bf16 v[88:91], v[136:139], v[200:203], v[88:91]
	v_mfma_f32_16x16x32_bf16 v[76:79], v[128:131], v[208:211], v[76:79]
	v_mfma_f32_16x16x32_bf16 v[72:75], v[136:139], v[208:211], v[72:75]
	v_mfma_f32_16x16x32_bf16 v[124:127], v[132:135], v[188:191], v[124:127]
	v_mfma_f32_16x16x32_bf16 v[120:123], v[140:143], v[188:191], v[120:123]
	v_mfma_f32_16x16x32_bf16 v[108:111], v[132:135], v[196:199], v[108:111]
	v_mfma_f32_16x16x32_bf16 v[104:107], v[140:143], v[196:199], v[104:107]
	v_mfma_f32_16x16x32_bf16 v[92:95], v[132:135], v[204:207], v[92:95]
	v_mfma_f32_16x16x32_bf16 v[88:91], v[140:143], v[204:207], v[88:91]
	v_mfma_f32_16x16x32_bf16 v[76:79], v[132:135], v[212:215], v[76:79]
	v_mfma_f32_16x16x32_bf16 v[72:75], v[140:143], v[212:215], v[72:75]
	s_setprio 0
	s_setprio 1
	v_mfma_f32_16x16x32_bf16 v[116:119], v[162:165], v[184:187], v[116:119]
	v_mfma_f32_16x16x32_bf16 v[112:115], v[176:179], v[184:187], v[112:115]
	v_mfma_f32_16x16x32_bf16 v[100:103], v[162:165], v[192:195], v[100:103]
	v_mfma_f32_16x16x32_bf16 v[96:99], v[176:179], v[192:195], v[96:99]
	v_mfma_f32_16x16x32_bf16 v[84:87], v[162:165], v[200:203], v[84:87]
	v_mfma_f32_16x16x32_bf16 v[80:83], v[176:179], v[200:203], v[80:83]
	v_mfma_f32_16x16x32_bf16 v[68:71], v[162:165], v[208:211], v[68:71]
	v_mfma_f32_16x16x32_bf16 v[64:67], v[176:179], v[208:211], v[64:67]
	v_mfma_f32_16x16x32_bf16 v[116:119], v[166:169], v[188:191], v[116:119]
	v_mfma_f32_16x16x32_bf16 v[112:115], v[180:183], v[188:191], v[112:115]
	v_mfma_f32_16x16x32_bf16 v[100:103], v[166:169], v[196:199], v[100:103]
	v_mfma_f32_16x16x32_bf16 v[96:99], v[180:183], v[196:199], v[96:99]
	v_mfma_f32_16x16x32_bf16 v[84:87], v[166:169], v[204:207], v[84:87]
	v_mfma_f32_16x16x32_bf16 v[80:83], v[180:183], v[204:207], v[80:83]
	v_mfma_f32_16x16x32_bf16 v[68:71], v[166:169], v[212:215], v[68:71]
	v_mfma_f32_16x16x32_bf16 v[64:67], v[180:183], v[212:215], v[64:67]
	s_setprio 0
	s_barrier
	s_add_i32 s8, s89, s43
	v_lshl_add_u64 v[216:217], v[216:217], 0, s[72:73]
	s_mov_b32 m0, s8
	ds_read_b128 v[184:187], v175 offset:49152
	ds_read_b128 v[188:191], v175 offset:50176
	ds_read_b128 v[192:195], v175 offset:51200
	ds_read_b128 v[196:199], v175 offset:52224
	ds_read_b128 v[200:203], v175 offset:53248
	ds_read_b128 v[204:207], v175 offset:54272
	ds_read_b128 v[208:211], v175 offset:55296
	ds_read_b128 v[212:215], v175 offset:56320
	global_load_lds_dwordx4 v[216:217], off
	s_add_i32 m0, s8, 0x2000
	s_add_u32 s6, s6, 0x80080
	v_lshl_add_u64 v[216:217], v[218:219], 0, s[72:73]
	s_addc_u32 s7, s7, 0
	s_add_i32 s8, s90, s43
	global_load_lds_dwordx4 v[216:217], off
	v_lshl_add_u64 v[216:217], s[6:7], 0, v[144:145]
	s_mov_b32 m0, s8
	s_nop 0
	global_load_lds_dwordx4 v[216:217], off
	v_lshl_add_u64 v[216:217], s[6:7], 0, v[146:147]
	s_add_i32 m0, s8, 0x2000
	s_nop 0
	global_load_lds_dwordx4 v[216:217], off
	v_lshl_add_u64 v[216:217], v[220:221], 0, s[72:73]
	s_mov_b32 m0, s49
	s_nop 0
	global_load_lds_dwordx4 v[216:217], off
	v_lshl_add_u64 v[216:217], v[222:223], 0, s[72:73]
	s_mov_b32 m0, s50
	s_nop 0
	global_load_lds_dwordx4 v[216:217], off
	s_waitcnt vmcnt(8)
	s_waitcnt lgkmcnt(0)
	s_barrier
	s_setprio 1
	s_waitcnt lgkmcnt(0)
	v_mfma_f32_16x16x32_bf16 v[60:63], v[128:131], v[184:187], v[60:63]
	v_mfma_f32_16x16x32_bf16 v[56:59], v[136:139], v[184:187], v[56:59]
	v_mfma_f32_16x16x32_bf16 v[44:47], v[128:131], v[192:195], v[44:47]
	v_mfma_f32_16x16x32_bf16 v[40:43], v[136:139], v[192:195], v[40:43]
	v_mfma_f32_16x16x32_bf16 v[28:31], v[128:131], v[200:203], v[28:31]
	v_mfma_f32_16x16x32_bf16 v[24:27], v[136:139], v[200:203], v[24:27]
	v_mfma_f32_16x16x32_bf16 v[12:15], v[128:131], v[208:211], v[12:15]
	v_mfma_f32_16x16x32_bf16 v[8:11], v[136:139], v[208:211], v[8:11]
	v_mfma_f32_16x16x32_bf16 v[60:63], v[132:135], v[188:191], v[60:63]
	v_mfma_f32_16x16x32_bf16 v[56:59], v[140:143], v[188:191], v[56:59]
	v_mfma_f32_16x16x32_bf16 v[44:47], v[132:135], v[196:199], v[44:47]
	v_mfma_f32_16x16x32_bf16 v[40:43], v[140:143], v[196:199], v[40:43]
	v_mfma_f32_16x16x32_bf16 v[28:31], v[132:135], v[204:207], v[28:31]
	v_mfma_f32_16x16x32_bf16 v[24:27], v[140:143], v[204:207], v[24:27]
	v_mfma_f32_16x16x32_bf16 v[12:15], v[132:135], v[212:215], v[12:15]
	v_mfma_f32_16x16x32_bf16 v[8:11], v[140:143], v[212:215], v[8:11]
	s_setprio 0
	s_setprio 1
	v_mfma_f32_16x16x32_bf16 v[52:55], v[162:165], v[184:187], v[52:55]
	v_mfma_f32_16x16x32_bf16 v[48:51], v[176:179], v[184:187], v[48:51]
	v_mfma_f32_16x16x32_bf16 v[36:39], v[162:165], v[192:195], v[36:39]
	v_mfma_f32_16x16x32_bf16 v[32:35], v[176:179], v[192:195], v[32:35]
	v_mfma_f32_16x16x32_bf16 v[20:23], v[162:165], v[200:203], v[20:23]
	v_mfma_f32_16x16x32_bf16 v[16:19], v[176:179], v[200:203], v[16:19]
	v_mfma_f32_16x16x32_bf16 v[4:7], v[162:165], v[208:211], v[4:7]
	v_mfma_f32_16x16x32_bf16 v[0:3], v[176:179], v[208:211], v[0:3]
	v_mfma_f32_16x16x32_bf16 v[52:55], v[166:169], v[188:191], v[52:55]
	v_mfma_f32_16x16x32_bf16 v[48:51], v[180:183], v[188:191], v[48:51]
	v_mfma_f32_16x16x32_bf16 v[36:39], v[166:169], v[196:199], v[36:39]
	v_mfma_f32_16x16x32_bf16 v[32:35], v[180:183], v[196:199], v[32:35]
	v_mfma_f32_16x16x32_bf16 v[20:23], v[166:169], v[204:207], v[20:23]
	v_mfma_f32_16x16x32_bf16 v[16:19], v[180:183], v[204:207], v[16:19]
	v_mfma_f32_16x16x32_bf16 v[4:7], v[166:169], v[212:215], v[4:7]
	v_mfma_f32_16x16x32_bf16 v[0:3], v[180:183], v[212:215], v[0:3]
	s_setprio 0
	s_barrier
	s_add_i32 s85, s85, 2
	s_add_u32 s4, s4, 0x100
	s_addc_u32 s5, s5, 0
	s_add_u32 s77, s77, 0x100
	s_addc_u32 s84, s84, 0
	s_cmp_gt_u32 s85, 29
	s_cbranch_scc0 .LBB0_468
	s_and_b64 vcc, exec, s[74:75]
	s_cbranch_vccz .LBB0_471
	s_barrier

.LBB0_797:
	ds_read_b128 v[152:155], v146
	ds_read_b128 v[156:159], v146 offset:1024
	ds_read_b128 v[160:163], v146 offset:2048
	ds_read_b128 v[164:167], v146 offset:3072
	ds_read_b128 v[168:171], v147
	ds_read_b128 v[172:175], v147 offset:1024
	ds_read_b128 v[176:179], v147 offset:2048
	ds_read_b128 v[180:183], v147 offset:3072
	s_add_u32 s22, s20, 0xf8980080
	s_addc_u32 s23, s21, -1
	s_cmp_lg_u32 s46, 28
	s_cselect_b32 s22, s22, 0
	s_cselect_b32 s23, s23, 0
	s_add_u32 s24, s12, s22
	s_addc_u32 s25, s13, s23
	s_add_u32 s22, s6, s22
	s_addc_u32 s23, s7, s23
	s_mov_b32 m0, s47
	v_lshl_add_u64 v[216:217], v[138:139], 0, s[20:21]
	ds_read_b128 v[184:187], v148
	ds_read_b128 v[188:191], v148 offset:1024
	ds_read_b128 v[192:195], v148 offset:2048
	ds_read_b128 v[196:199], v148 offset:3072
	ds_read_b128 v[200:203], v148 offset:4096
	ds_read_b128 v[204:207], v148 offset:5120
	ds_read_b128 v[208:211], v148 offset:6144
	ds_read_b128 v[212:215], v148 offset:7168
	global_load_lds_dwordx4 v[216:217], off
	v_lshl_add_u64 v[216:217], v[140:141], 0, s[20:21]
	s_mov_b32 m0, s48
	s_nop 0
	global_load_lds_dwordx4 v[216:217], off
	s_waitcnt vmcnt(8)
	s_waitcnt lgkmcnt(0)
	s_barrier
	s_setprio 1
	s_waitcnt lgkmcnt(0)
	s_nop 0
	v_mfma_f32_16x16x32_bf16 v[124:127], v[152:155], v[184:187], v[124:127]
	v_mfma_f32_16x16x32_bf16 v[120:123], v[160:163], v[184:187], v[120:123]
	v_mfma_f32_16x16x32_bf16 v[108:111], v[152:155], v[192:195], v[108:111]
	v_mfma_f32_16x16x32_bf16 v[104:107], v[160:163], v[192:195], v[104:107]
	v_mfma_f32_16x16x32_bf16 v[92:95], v[152:155], v[200:203], v[92:95]
	v_mfma_f32_16x16x32_bf16 v[88:91], v[160:163], v[200:203], v[88:91]
	v_mfma_f32_16x16x32_bf16 v[76:79], v[152:155], v[208:211], v[76:79]
	v_mfma_f32_16x16x32_bf16 v[72:75], v[160:163], v[208:211], v[72:75]
	v_mfma_f32_16x16x32_bf16 v[124:127], v[156:159], v[188:191], v[124:127]
	v_mfma_f32_16x16x32_bf16 v[120:123], v[164:167], v[188:191], v[120:123]
	v_mfma_f32_16x16x32_bf16 v[108:111], v[156:159], v[196:199], v[108:111]
	v_mfma_f32_16x16x32_bf16 v[104:107], v[164:167], v[196:199], v[104:107]
	v_mfma_f32_16x16x32_bf16 v[92:95], v[156:159], v[204:207], v[92:95]
	v_mfma_f32_16x16x32_bf16 v[88:91], v[164:167], v[204:207], v[88:91]
	v_mfma_f32_16x16x32_bf16 v[76:79], v[156:159], v[212:215], v[76:79]
	v_mfma_f32_16x16x32_bf16 v[72:75], v[164:167], v[212:215], v[72:75]
	s_setprio 0
	s_setprio 1
	v_mfma_f32_16x16x32_bf16 v[116:119], v[168:171], v[184:187], v[116:119]
	v_mfma_f32_16x16x32_bf16 v[112:115], v[176:179], v[184:187], v[112:115]
	v_mfma_f32_16x16x32_bf16 v[100:103], v[168:171], v[192:195], v[100:103]
	v_mfma_f32_16x16x32_bf16 v[96:99], v[176:179], v[192:195], v[96:99]
	v_mfma_f32_16x16x32_bf16 v[84:87], v[168:171], v[200:203], v[84:87]
	v_mfma_f32_16x16x32_bf16 v[80:83], v[176:179], v[200:203], v[80:83]
	v_mfma_f32_16x16x32_bf16 v[68:71], v[168:171], v[208:211], v[68:71]
	v_mfma_f32_16x16x32_bf16 v[64:67], v[176:179], v[208:211], v[64:67]
	v_mfma_f32_16x16x32_bf16 v[116:119], v[172:175], v[188:191], v[116:119]
	v_mfma_f32_16x16x32_bf16 v[112:115], v[180:183], v[188:191], v[112:115]
	v_mfma_f32_16x16x32_bf16 v[100:103], v[172:175], v[196:199], v[100:103]
	v_mfma_f32_16x16x32_bf16 v[96:99], v[180:183], v[196:199], v[96:99]
	v_mfma_f32_16x16x32_bf16 v[84:87], v[172:175], v[204:207], v[84:87]
	v_mfma_f32_16x16x32_bf16 v[80:83], v[180:183], v[204:207], v[80:83]
	v_mfma_f32_16x16x32_bf16 v[68:71], v[172:175], v[212:215], v[68:71]
	v_mfma_f32_16x16x32_bf16 v[64:67], v[180:183], v[212:215], v[64:67]
	s_setprio 0
	s_barrier
	s_mov_b32 m0, s49
	v_lshl_add_u64 v[216:217], s[22:23], 0, v[128:129]
	s_add_u32 s86, s22, 0x80000
	ds_read_b128 v[184:187], v148 offset:16384
	ds_read_b128 v[188:191], v148 offset:17408
	ds_read_b128 v[192:195], v148 offset:18432
	ds_read_b128 v[196:199], v148 offset:19456
	ds_read_b128 v[200:203], v148 offset:20480
	ds_read_b128 v[204:207], v148 offset:21504
	ds_read_b128 v[208:211], v148 offset:22528
	ds_read_b128 v[212:215], v148 offset:23552
	global_load_lds_dwordx4 v[216:217], off
	v_lshl_add_u64 v[218:219], s[22:23], 0, v[130:131]
	s_mov_b32 m0, s50
	s_addc_u32 s87, s23, 0
	global_load_lds_dwordx4 v[218:219], off
	v_lshl_add_u64 v[220:221], s[86:87], 0, v[128:129]
	s_mov_b32 m0, s51
	v_lshl_add_u64 v[222:223], s[24:25], 0, v[130:131]
	global_load_lds_dwordx4 v[220:221], off
	v_lshl_add_u64 v[220:221], s[86:87], 0, v[130:131]
	s_mov_b32 m0, s56
	s_nop 0
	global_load_lds_dwordx4 v[220:221], off
	v_lshl_add_u64 v[220:221], s[24:25], 0, v[128:129]
	s_mov_b32 m0, s5
	s_nop 0
	global_load_lds_dwordx4 v[220:221], off
	s_mov_b32 m0, s39
	s_nop 0
	global_load_lds_dwordx4 v[222:223], off
	s_waitcnt vmcnt(8)
	s_waitcnt lgkmcnt(0)
	s_barrier
	s_setprio 1
	s_waitcnt lgkmcnt(0)
	s_nop 0
	v_mfma_f32_16x16x32_bf16 v[60:63], v[152:155], v[184:187], v[60:63]
	v_mfma_f32_16x16x32_bf16 v[56:59], v[160:163], v[184:187], v[56:59]
	v_mfma_f32_16x16x32_bf16 v[44:47], v[152:155], v[192:195], v[44:47]
	v_mfma_f32_16x16x32_bf16 v[40:43], v[160:163], v[192:195], v[40:43]
	v_mfma_f32_16x16x32_bf16 v[28:31], v[152:155], v[200:203], v[28:31]
	v_mfma_f32_16x16x32_bf16 v[24:27], v[160:163], v[200:203], v[24:27]
	v_mfma_f32_16x16x32_bf16 v[12:15], v[152:155], v[208:211], v[12:15]
	v_mfma_f32_16x16x32_bf16 v[8:11], v[160:163], v[208:211], v[8:11]
	v_mfma_f32_16x16x32_bf16 v[60:63], v[156:159], v[188:191], v[60:63]
	v_mfma_f32_16x16x32_bf16 v[56:59], v[164:167], v[188:191], v[56:59]
	v_mfma_f32_16x16x32_bf16 v[44:47], v[156:159], v[196:199], v[44:47]
	v_mfma_f32_16x16x32_bf16 v[40:43], v[164:167], v[196:199], v[40:43]
	v_mfma_f32_16x16x32_bf16 v[28:31], v[156:159], v[204:207], v[28:31]
	v_mfma_f32_16x16x32_bf16 v[24:27], v[164:167], v[204:207], v[24:27]
	v_mfma_f32_16x16x32_bf16 v[12:15], v[156:159], v[212:215], v[12:15]
	v_mfma_f32_16x16x32_bf16 v[8:11], v[164:167], v[212:215], v[8:11]
	s_setprio 0
	s_setprio 1
	v_mfma_f32_16x16x32_bf16 v[52:55], v[168:171], v[184:187], v[52:55]
	v_mfma_f32_16x16x32_bf16 v[48:51], v[176:179], v[184:187], v[48:51]
	v_mfma_f32_16x16x32_bf16 v[36:39], v[168:171], v[192:195], v[36:39]
	v_mfma_f32_16x16x32_bf16 v[32:35], v[176:179], v[192:195], v[32:35]
	v_mfma_f32_16x16x32_bf16 v[20:23], v[168:171], v[200:203], v[20:23]
	v_mfma_f32_16x16x32_bf16 v[16:19], v[176:179], v[200:203], v[16:19]
	v_mfma_f32_16x16x32_bf16 v[4:7], v[168:171], v[208:211], v[4:7]
	v_mfma_f32_16x16x32_bf16 v[0:3], v[176:179], v[208:211], v[0:3]
	v_mfma_f32_16x16x32_bf16 v[52:55], v[172:175], v[188:191], v[52:55]
	v_mfma_f32_16x16x32_bf16 v[48:51], v[180:183], v[188:191], v[48:51]
	v_mfma_f32_16x16x32_bf16 v[36:39], v[172:175], v[196:199], v[36:39]
	v_mfma_f32_16x16x32_bf16 v[32:35], v[180:183], v[196:199], v[32:35]
	v_mfma_f32_16x16x32_bf16 v[20:23], v[172:175], v[204:207], v[20:23]
	v_mfma_f32_16x16x32_bf16 v[16:19], v[180:183], v[204:207], v[16:19]
	v_mfma_f32_16x16x32_bf16 v[4:7], v[172:175], v[212:215], v[4:7]
	v_mfma_f32_16x16x32_bf16 v[0:3], v[180:183], v[212:215], v[0:3]
	s_setprio 0
	s_barrier
	ds_read_b128 v[152:155], v149
	ds_read_b128 v[156:159], v149 offset:1024
	ds_read_b128 v[160:163], v149 offset:2048
	ds_read_b128 v[164:167], v149 offset:3072
	ds_read_b128 v[168:171], v150
	ds_read_b128 v[172:175], v150 offset:1024
	ds_read_b128 v[176:179], v150 offset:2048
	ds_read_b128 v[180:183], v150 offset:3072
	s_add_u32 s24, s24, 0x80000
	s_addc_u32 s25, s25, 0
	s_mov_b32 m0, s40
	v_lshl_add_u64 v[224:225], s[24:25], 0, v[128:129]
	ds_read_b128 v[184:187], v148 offset:32768
	ds_read_b128 v[188:191], v148 offset:33792
	ds_read_b128 v[192:195], v148 offset:34816
	ds_read_b128 v[196:199], v148 offset:35840
	ds_read_b128 v[200:203], v148 offset:36864
	ds_read_b128 v[204:207], v148 offset:37888
	ds_read_b128 v[208:211], v148 offset:38912
	ds_read_b128 v[212:215], v148 offset:39936
	global_load_lds_dwordx4 v[224:225], off
	v_lshl_add_u64 v[224:225], s[24:25], 0, v[130:131]
	s_mov_b32 m0, s42
	s_nop 0
	global_load_lds_dwordx4 v[224:225], off
	s_waitcnt vmcnt(8)
	s_waitcnt lgkmcnt(0)
	s_barrier
	s_setprio 1
	s_waitcnt lgkmcnt(0)
	s_nop 0
	v_mfma_f32_16x16x32_bf16 v[124:127], v[152:155], v[184:187], v[124:127]
	v_mfma_f32_16x16x32_bf16 v[120:123], v[160:163], v[184:187], v[120:123]
	v_mfma_f32_16x16x32_bf16 v[108:111], v[152:155], v[192:195], v[108:111]
	v_mfma_f32_16x16x32_bf16 v[104:107], v[160:163], v[192:195], v[104:107]
	v_mfma_f32_16x16x32_bf16 v[92:95], v[152:155], v[200:203], v[92:95]
	v_mfma_f32_16x16x32_bf16 v[88:91], v[160:163], v[200:203], v[88:91]
	v_mfma_f32_16x16x32_bf16 v[76:79], v[152:155], v[208:211], v[76:79]
	v_mfma_f32_16x16x32_bf16 v[72:75], v[160:163], v[208:211], v[72:75]
	v_mfma_f32_16x16x32_bf16 v[124:127], v[156:159], v[188:191], v[124:127]
	v_mfma_f32_16x16x32_bf16 v[120:123], v[164:167], v[188:191], v[120:123]
	v_mfma_f32_16x16x32_bf16 v[108:111], v[156:159], v[196:199], v[108:111]
	v_mfma_f32_16x16x32_bf16 v[104:107], v[164:167], v[196:199], v[104:107]
	v_mfma_f32_16x16x32_bf16 v[92:95], v[156:159], v[204:207], v[92:95]
	v_mfma_f32_16x16x32_bf16 v[88:91], v[164:167], v[204:207], v[88:91]
	v_mfma_f32_16x16x32_bf16 v[76:79], v[156:159], v[212:215], v[76:79]
	v_mfma_f32_16x16x32_bf16 v[72:75], v[164:167], v[212:215], v[72:75]
	s_setprio 0
	s_setprio 1
	v_mfma_f32_16x16x32_bf16 v[116:119], v[168:171], v[184:187], v[116:119]
	v_mfma_f32_16x16x32_bf16 v[112:115], v[176:179], v[184:187], v[112:115]
	v_mfma_f32_16x16x32_bf16 v[100:103], v[168:171], v[192:195], v[100:103]
	v_mfma_f32_16x16x32_bf16 v[96:99], v[176:179], v[192:195], v[96:99]
	v_mfma_f32_16x16x32_bf16 v[84:87], v[168:171], v[200:203], v[84:87]
	v_mfma_f32_16x16x32_bf16 v[80:83], v[176:179], v[200:203], v[80:83]
	v_mfma_f32_16x16x32_bf16 v[68:71], v[168:171], v[208:211], v[68:71]
	v_mfma_f32_16x16x32_bf16 v[64:67], v[176:179], v[208:211], v[64:67]
	v_mfma_f32_16x16x32_bf16 v[116:119], v[172:175], v[188:191], v[116:119]
	v_mfma_f32_16x16x32_bf16 v[112:115], v[180:183], v[188:191], v[112:115]
	v_mfma_f32_16x16x32_bf16 v[100:103], v[172:175], v[196:199], v[100:103]
	v_mfma_f32_16x16x32_bf16 v[96:99], v[180:183], v[196:199], v[96:99]
	v_mfma_f32_16x16x32_bf16 v[84:87], v[172:175], v[204:207], v[84:87]
	v_mfma_f32_16x16x32_bf16 v[80:83], v[180:183], v[204:207], v[80:83]
	v_mfma_f32_16x16x32_bf16 v[68:71], v[172:175], v[212:215], v[68:71]
	v_mfma_f32_16x16x32_bf16 v[64:67], v[180:183], v[212:215], v[64:67]
	s_setprio 0
	s_barrier
	s_mov_b32 m0, s57
	v_lshl_add_u64 v[216:217], v[216:217], 0, s[2:3]
	s_add_u32 s22, s22, 0x80080
	ds_read_b128 v[184:187], v148 offset:49152
	ds_read_b128 v[188:191], v148 offset:50176
	ds_read_b128 v[192:195], v148 offset:51200
	ds_read_b128 v[196:199], v148 offset:52224
	ds_read_b128 v[200:203], v148 offset:53248
	ds_read_b128 v[204:207], v148 offset:54272
	ds_read_b128 v[208:211], v148 offset:55296
	ds_read_b128 v[212:215], v148 offset:56320
	global_load_lds_dwordx4 v[216:217], off
	v_lshl_add_u64 v[216:217], v[218:219], 0, s[2:3]
	s_mov_b32 m0, s58
	s_addc_u32 s23, s23, 0
	global_load_lds_dwordx4 v[216:217], off
	v_lshl_add_u64 v[216:217], s[22:23], 0, v[128:129]
	s_mov_b32 m0, s59
	s_nop 0
	global_load_lds_dwordx4 v[216:217], off
	v_lshl_add_u64 v[216:217], s[22:23], 0, v[130:131]
	s_mov_b32 m0, s84
	s_nop 0
	global_load_lds_dwordx4 v[216:217], off
	v_lshl_add_u64 v[216:217], v[220:221], 0, s[2:3]
	s_mov_b32 m0, s44
	s_nop 0
	global_load_lds_dwordx4 v[216:217], off
	v_lshl_add_u64 v[216:217], v[222:223], 0, s[2:3]
	s_mov_b32 m0, s45
	s_nop 0
	global_load_lds_dwordx4 v[216:217], off
	s_waitcnt vmcnt(8)
	s_waitcnt lgkmcnt(0)
	s_barrier
	s_setprio 1
	s_waitcnt lgkmcnt(0)
	v_mfma_f32_16x16x32_bf16 v[60:63], v[152:155], v[184:187], v[60:63]
	v_mfma_f32_16x16x32_bf16 v[56:59], v[160:163], v[184:187], v[56:59]
	v_mfma_f32_16x16x32_bf16 v[44:47], v[152:155], v[192:195], v[44:47]
	v_mfma_f32_16x16x32_bf16 v[40:43], v[160:163], v[192:195], v[40:43]
	v_mfma_f32_16x16x32_bf16 v[28:31], v[152:155], v[200:203], v[28:31]
	v_mfma_f32_16x16x32_bf16 v[24:27], v[160:163], v[200:203], v[24:27]
	v_mfma_f32_16x16x32_bf16 v[12:15], v[152:155], v[208:211], v[12:15]
	v_mfma_f32_16x16x32_bf16 v[8:11], v[160:163], v[208:211], v[8:11]
	v_mfma_f32_16x16x32_bf16 v[60:63], v[156:159], v[188:191], v[60:63]
	v_mfma_f32_16x16x32_bf16 v[56:59], v[164:167], v[188:191], v[56:59]
	v_mfma_f32_16x16x32_bf16 v[44:47], v[156:159], v[196:199], v[44:47]
	v_mfma_f32_16x16x32_bf16 v[40:43], v[164:167], v[196:199], v[40:43]
	v_mfma_f32_16x16x32_bf16 v[28:31], v[156:159], v[204:207], v[28:31]
	v_mfma_f32_16x16x32_bf16 v[24:27], v[164:167], v[204:207], v[24:27]
	v_mfma_f32_16x16x32_bf16 v[12:15], v[156:159], v[212:215], v[12:15]
	v_mfma_f32_16x16x32_bf16 v[8:11], v[164:167], v[212:215], v[8:11]
	s_setprio 0
	s_setprio 1
	v_mfma_f32_16x16x32_bf16 v[52:55], v[168:171], v[184:187], v[52:55]
	v_mfma_f32_16x16x32_bf16 v[48:51], v[176:179], v[184:187], v[48:51]
	v_mfma_f32_16x16x32_bf16 v[36:39], v[168:171], v[192:195], v[36:39]
	v_mfma_f32_16x16x32_bf16 v[32:35], v[176:179], v[192:195], v[32:35]
	v_mfma_f32_16x16x32_bf16 v[20:23], v[168:171], v[200:203], v[20:23]
	v_mfma_f32_16x16x32_bf16 v[16:19], v[176:179], v[200:203], v[16:19]
	v_mfma_f32_16x16x32_bf16 v[4:7], v[168:171], v[208:211], v[4:7]
	v_mfma_f32_16x16x32_bf16 v[0:3], v[176:179], v[208:211], v[0:3]
	v_mfma_f32_16x16x32_bf16 v[52:55], v[172:175], v[188:191], v[52:55]
	v_mfma_f32_16x16x32_bf16 v[48:51], v[180:183], v[188:191], v[48:51]
	v_mfma_f32_16x16x32_bf16 v[36:39], v[172:175], v[196:199], v[36:39]
	v_mfma_f32_16x16x32_bf16 v[32:35], v[180:183], v[196:199], v[32:35]
	v_mfma_f32_16x16x32_bf16 v[20:23], v[172:175], v[204:207], v[20:23]
	v_mfma_f32_16x16x32_bf16 v[16:19], v[180:183], v[204:207], v[16:19]
	v_mfma_f32_16x16x32_bf16 v[4:7], v[172:175], v[212:215], v[4:7]
	v_mfma_f32_16x16x32_bf16 v[0:3], v[180:183], v[212:215], v[0:3]
	s_setprio 0
	s_barrier
	s_add_i32 s46, s46, 2
	s_add_u32 s20, s20, 0x100
	s_addc_u32 s21, s21, 0
	s_cmp_gt_u32 s46, 29
	s_cbranch_scc0 .LBB0_797
	s_cmpk_lt_u32 s38, 0x100
	s_cbranch_scc0 .LBB0_800
	s_barrier

.LBB0_1058:
	ds_read_b128 v[136:139], v143
	ds_read_b128 v[146:149], v143 offset:1024
	ds_read_b128 v[150:153], v143 offset:2048
	ds_read_b128 v[154:157], v143 offset:3072
	ds_read_b128 v[158:161], v144
	ds_read_b128 v[162:165], v144 offset:1024
	ds_read_b128 v[166:169], v144 offset:2048
	ds_read_b128 v[170:173], v144 offset:3072
	s_add_u32 s26, s24, 0xfffc0080
	s_addc_u32 s27, s25, -1
	s_cmp_eq_u32 s56, 12
	s_cselect_b32 s29, s46, s27
	s_cselect_b32 s28, s47, s26
	s_cselect_b32 s27, s48, s51
	s_cselect_b32 s26, s49, s50
	v_lshl_add_u64 v[206:207], s[24:25], 0, v[132:133]
	s_add_i32 m0, s35, 0xc000
	ds_read_b128 v[174:177], v145
	ds_read_b128 v[178:181], v145 offset:1024
	ds_read_b128 v[182:185], v145 offset:2048
	ds_read_b128 v[186:189], v145 offset:3072
	ds_read_b128 v[190:193], v145 offset:4096
	ds_read_b128 v[194:197], v145 offset:5120
	ds_read_b128 v[198:201], v145 offset:6144
	ds_read_b128 v[202:205], v145 offset:7168
	global_load_lds_dwordx4 v[206:207], off
	v_lshl_add_u64 v[206:207], s[24:25], 0, v[134:135]
	s_add_i32 m0, s35, 0xe000
	s_nop 0
	global_load_lds_dwordx4 v[206:207], off
	s_waitcnt vmcnt(8)
	s_waitcnt lgkmcnt(0)
	s_barrier
	s_setprio 1
	s_waitcnt lgkmcnt(0)
	v_mfma_f32_16x16x32_bf16 v[124:127], v[136:139], v[174:177], v[124:127]
	v_mfma_f32_16x16x32_bf16 v[120:123], v[150:153], v[174:177], v[120:123]
	v_mfma_f32_16x16x32_bf16 v[108:111], v[136:139], v[182:185], v[108:111]
	v_mfma_f32_16x16x32_bf16 v[104:107], v[150:153], v[182:185], v[104:107]
	v_mfma_f32_16x16x32_bf16 v[92:95], v[136:139], v[190:193], v[92:95]
	v_mfma_f32_16x16x32_bf16 v[88:91], v[150:153], v[190:193], v[88:91]
	v_mfma_f32_16x16x32_bf16 v[76:79], v[136:139], v[198:201], v[76:79]
	v_mfma_f32_16x16x32_bf16 v[72:75], v[150:153], v[198:201], v[72:75]
	v_mfma_f32_16x16x32_bf16 v[124:127], v[146:149], v[178:181], v[124:127]
	v_mfma_f32_16x16x32_bf16 v[120:123], v[154:157], v[178:181], v[120:123]
	v_mfma_f32_16x16x32_bf16 v[108:111], v[146:149], v[186:189], v[108:111]
	v_mfma_f32_16x16x32_bf16 v[104:107], v[154:157], v[186:189], v[104:107]
	v_mfma_f32_16x16x32_bf16 v[92:95], v[146:149], v[194:197], v[92:95]
	v_mfma_f32_16x16x32_bf16 v[88:91], v[154:157], v[194:197], v[88:91]
	v_mfma_f32_16x16x32_bf16 v[76:79], v[146:149], v[202:205], v[76:79]
	v_mfma_f32_16x16x32_bf16 v[72:75], v[154:157], v[202:205], v[72:75]
	s_setprio 0
	s_setprio 1
	v_mfma_f32_16x16x32_bf16 v[116:119], v[158:161], v[174:177], v[116:119]
	v_mfma_f32_16x16x32_bf16 v[112:115], v[166:169], v[174:177], v[112:115]
	v_mfma_f32_16x16x32_bf16 v[100:103], v[158:161], v[182:185], v[100:103]
	v_mfma_f32_16x16x32_bf16 v[96:99], v[166:169], v[182:185], v[96:99]
	v_mfma_f32_16x16x32_bf16 v[84:87], v[158:161], v[190:193], v[84:87]
	v_mfma_f32_16x16x32_bf16 v[80:83], v[166:169], v[190:193], v[80:83]
	v_mfma_f32_16x16x32_bf16 v[68:71], v[158:161], v[198:201], v[68:71]
	v_mfma_f32_16x16x32_bf16 v[64:67], v[166:169], v[198:201], v[64:67]
	v_mfma_f32_16x16x32_bf16 v[116:119], v[162:165], v[178:181], v[116:119]
	v_mfma_f32_16x16x32_bf16 v[112:115], v[170:173], v[178:181], v[112:115]
	v_mfma_f32_16x16x32_bf16 v[100:103], v[162:165], v[186:189], v[100:103]
	v_mfma_f32_16x16x32_bf16 v[96:99], v[170:173], v[186:189], v[96:99]
	v_mfma_f32_16x16x32_bf16 v[84:87], v[162:165], v[194:197], v[84:87]
	v_mfma_f32_16x16x32_bf16 v[80:83], v[170:173], v[194:197], v[80:83]
	v_mfma_f32_16x16x32_bf16 v[68:71], v[162:165], v[202:205], v[68:71]
	v_mfma_f32_16x16x32_bf16 v[64:67], v[170:173], v[202:205], v[64:67]
	s_setprio 0
	s_barrier
	s_add_i32 s57, s42, s33
	v_lshl_add_u64 v[206:207], s[26:27], 0, v[130:131]
	s_mov_b32 m0, s57
	ds_read_b128 v[174:177], v145 offset:16384
	ds_read_b128 v[178:181], v145 offset:17408
	ds_read_b128 v[182:185], v145 offset:18432
	ds_read_b128 v[186:189], v145 offset:19456
	ds_read_b128 v[190:193], v145 offset:20480
	ds_read_b128 v[194:197], v145 offset:21504
	ds_read_b128 v[198:201], v145 offset:22528
	ds_read_b128 v[202:205], v145 offset:23552
	global_load_lds_dwordx4 v[206:207], off
	s_add_i32 m0, s57, 0x2000
	s_add_u32 s58, s26, 0x40000
	v_lshl_add_u64 v[208:209], s[26:27], 0, v[128:129]
	s_addc_u32 s59, s27, 0
	s_add_i32 s57, s43, s33
	global_load_lds_dwordx4 v[208:209], off
	v_lshl_add_u64 v[210:211], s[58:59], 0, v[130:131]
	s_mov_b32 m0, s57
	v_lshl_add_u64 v[212:213], s[28:29], 0, v[128:129]
	global_load_lds_dwordx4 v[210:211], off
	v_lshl_add_u64 v[210:211], s[58:59], 0, v[128:129]
	s_add_i32 m0, s57, 0x2000
	s_nop 0
	global_load_lds_dwordx4 v[210:211], off
	v_lshl_add_u64 v[210:211], s[28:29], 0, v[130:131]
	s_mov_b32 m0, s35
	s_nop 0
	global_load_lds_dwordx4 v[210:211], off
	s_mov_b32 m0, s36
	s_nop 0
	global_load_lds_dwordx4 v[212:213], off
	s_waitcnt vmcnt(8)
	s_waitcnt lgkmcnt(0)
	s_barrier
	s_setprio 1
	s_waitcnt lgkmcnt(0)
	s_nop 0
	v_mfma_f32_16x16x32_bf16 v[60:63], v[136:139], v[174:177], v[60:63]
	v_mfma_f32_16x16x32_bf16 v[56:59], v[150:153], v[174:177], v[56:59]
	v_mfma_f32_16x16x32_bf16 v[44:47], v[136:139], v[182:185], v[44:47]
	v_mfma_f32_16x16x32_bf16 v[40:43], v[150:153], v[182:185], v[40:43]
	v_mfma_f32_16x16x32_bf16 v[28:31], v[136:139], v[190:193], v[28:31]
	v_mfma_f32_16x16x32_bf16 v[24:27], v[150:153], v[190:193], v[24:27]
	v_mfma_f32_16x16x32_bf16 v[12:15], v[136:139], v[198:201], v[12:15]
	v_mfma_f32_16x16x32_bf16 v[8:11], v[150:153], v[198:201], v[8:11]
	v_mfma_f32_16x16x32_bf16 v[60:63], v[146:149], v[178:181], v[60:63]
	v_mfma_f32_16x16x32_bf16 v[56:59], v[154:157], v[178:181], v[56:59]
	v_mfma_f32_16x16x32_bf16 v[44:47], v[146:149], v[186:189], v[44:47]
	v_mfma_f32_16x16x32_bf16 v[40:43], v[154:157], v[186:189], v[40:43]
	v_mfma_f32_16x16x32_bf16 v[28:31], v[146:149], v[194:197], v[28:31]
	v_mfma_f32_16x16x32_bf16 v[24:27], v[154:157], v[194:197], v[24:27]
	v_mfma_f32_16x16x32_bf16 v[12:15], v[146:149], v[202:205], v[12:15]
	v_mfma_f32_16x16x32_bf16 v[8:11], v[154:157], v[202:205], v[8:11]
	s_setprio 0
	s_setprio 1
	v_mfma_f32_16x16x32_bf16 v[52:55], v[158:161], v[174:177], v[52:55]
	v_mfma_f32_16x16x32_bf16 v[48:51], v[166:169], v[174:177], v[48:51]
	v_mfma_f32_16x16x32_bf16 v[36:39], v[158:161], v[182:185], v[36:39]
	v_mfma_f32_16x16x32_bf16 v[32:35], v[166:169], v[182:185], v[32:35]
	v_mfma_f32_16x16x32_bf16 v[20:23], v[158:161], v[190:193], v[20:23]
	v_mfma_f32_16x16x32_bf16 v[16:19], v[166:169], v[190:193], v[16:19]
	v_mfma_f32_16x16x32_bf16 v[4:7], v[158:161], v[198:201], v[4:7]
	v_mfma_f32_16x16x32_bf16 v[0:3], v[166:169], v[198:201], v[0:3]
	v_mfma_f32_16x16x32_bf16 v[52:55], v[162:165], v[178:181], v[52:55]
	v_mfma_f32_16x16x32_bf16 v[48:51], v[170:173], v[178:181], v[48:51]
	v_mfma_f32_16x16x32_bf16 v[36:39], v[162:165], v[186:189], v[36:39]
	v_mfma_f32_16x16x32_bf16 v[32:35], v[170:173], v[186:189], v[32:35]
	v_mfma_f32_16x16x32_bf16 v[20:23], v[162:165], v[194:197], v[20:23]
	v_mfma_f32_16x16x32_bf16 v[16:19], v[170:173], v[194:197], v[16:19]
	v_mfma_f32_16x16x32_bf16 v[4:7], v[162:165], v[202:205], v[4:7]
	v_mfma_f32_16x16x32_bf16 v[0:3], v[170:173], v[202:205], v[0:3]
	s_setprio 0
	s_barrier
	s_add_i32 s57, 0, 0x18000
	s_add_i32 s58, 0, 0x1c000
	v_add_u32_e32 v154, s57, v141
	v_add_u32_e32 v170, s58, v141
	ds_read_b128 v[136:139], v154
	ds_read_b128 v[146:149], v154 offset:1024
	ds_read_b128 v[150:153], v154 offset:2048
	ds_read_b128 v[154:157], v154 offset:3072
	ds_read_b128 v[158:161], v170
	ds_read_b128 v[162:165], v170 offset:1024
	ds_read_b128 v[166:169], v170 offset:2048
	ds_read_b128 v[170:173], v170 offset:3072
	s_add_u32 s28, s28, 0x40000
	s_addc_u32 s29, s29, 0
	s_mov_b32 m0, s37
	v_lshl_add_u64 v[214:215], s[28:29], 0, v[130:131]
	ds_read_b128 v[174:177], v145 offset:32768
	ds_read_b128 v[178:181], v145 offset:33792
	ds_read_b128 v[182:185], v145 offset:34816
	ds_read_b128 v[186:189], v145 offset:35840
	ds_read_b128 v[190:193], v145 offset:36864
	ds_read_b128 v[194:197], v145 offset:37888
	ds_read_b128 v[198:201], v145 offset:38912
	ds_read_b128 v[202:205], v145 offset:39936
	global_load_lds_dwordx4 v[214:215], off
	v_lshl_add_u64 v[214:215], s[28:29], 0, v[128:129]
	s_mov_b32 m0, s38
	s_nop 0
	global_load_lds_dwordx4 v[214:215], off
	s_waitcnt vmcnt(8)
	s_waitcnt lgkmcnt(0)
	s_barrier
	s_setprio 1
	s_waitcnt lgkmcnt(0)
	s_nop 0
	v_mfma_f32_16x16x32_bf16 v[124:127], v[136:139], v[174:177], v[124:127]
	v_mfma_f32_16x16x32_bf16 v[120:123], v[150:153], v[174:177], v[120:123]
	v_mfma_f32_16x16x32_bf16 v[108:111], v[136:139], v[182:185], v[108:111]
	v_mfma_f32_16x16x32_bf16 v[104:107], v[150:153], v[182:185], v[104:107]
	v_mfma_f32_16x16x32_bf16 v[92:95], v[136:139], v[190:193], v[92:95]
	v_mfma_f32_16x16x32_bf16 v[88:91], v[150:153], v[190:193], v[88:91]
	v_mfma_f32_16x16x32_bf16 v[76:79], v[136:139], v[198:201], v[76:79]
	v_mfma_f32_16x16x32_bf16 v[72:75], v[150:153], v[198:201], v[72:75]
	v_mfma_f32_16x16x32_bf16 v[124:127], v[146:149], v[178:181], v[124:127]
	v_mfma_f32_16x16x32_bf16 v[120:123], v[154:157], v[178:181], v[120:123]
	v_mfma_f32_16x16x32_bf16 v[108:111], v[146:149], v[186:189], v[108:111]
	v_mfma_f32_16x16x32_bf16 v[104:107], v[154:157], v[186:189], v[104:107]
	v_mfma_f32_16x16x32_bf16 v[92:95], v[146:149], v[194:197], v[92:95]
	v_mfma_f32_16x16x32_bf16 v[88:91], v[154:157], v[194:197], v[88:91]
	v_mfma_f32_16x16x32_bf16 v[76:79], v[146:149], v[202:205], v[76:79]
	v_mfma_f32_16x16x32_bf16 v[72:75], v[154:157], v[202:205], v[72:75]
	s_setprio 0
	s_setprio 1
	v_mfma_f32_16x16x32_bf16 v[116:119], v[158:161], v[174:177], v[116:119]
	v_mfma_f32_16x16x32_bf16 v[112:115], v[166:169], v[174:177], v[112:115]
	v_mfma_f32_16x16x32_bf16 v[100:103], v[158:161], v[182:185], v[100:103]
	v_mfma_f32_16x16x32_bf16 v[96:99], v[166:169], v[182:185], v[96:99]
	v_mfma_f32_16x16x32_bf16 v[84:87], v[158:161], v[190:193], v[84:87]
	v_mfma_f32_16x16x32_bf16 v[80:83], v[166:169], v[190:193], v[80:83]
	v_mfma_f32_16x16x32_bf16 v[68:71], v[158:161], v[198:201], v[68:71]
	v_mfma_f32_16x16x32_bf16 v[64:67], v[166:169], v[198:201], v[64:67]
	v_mfma_f32_16x16x32_bf16 v[116:119], v[162:165], v[178:181], v[116:119]
	v_mfma_f32_16x16x32_bf16 v[112:115], v[170:173], v[178:181], v[112:115]
	v_mfma_f32_16x16x32_bf16 v[100:103], v[162:165], v[186:189], v[100:103]
	v_mfma_f32_16x16x32_bf16 v[96:99], v[170:173], v[186:189], v[96:99]
	v_mfma_f32_16x16x32_bf16 v[84:87], v[162:165], v[194:197], v[84:87]
	v_mfma_f32_16x16x32_bf16 v[80:83], v[170:173], v[194:197], v[80:83]
	v_mfma_f32_16x16x32_bf16 v[68:71], v[162:165], v[202:205], v[68:71]
	v_mfma_f32_16x16x32_bf16 v[64:67], v[170:173], v[202:205], v[64:67]
	s_setprio 0
	s_barrier
	s_add_i32 s28, s57, s33
	v_lshl_add_u64 v[206:207], v[206:207], 0, s[18:19]
	s_mov_b32 m0, s28
	ds_read_b128 v[174:177], v145 offset:49152
	ds_read_b128 v[178:181], v145 offset:50176
	ds_read_b128 v[182:185], v145 offset:51200
	ds_read_b128 v[186:189], v145 offset:52224
	ds_read_b128 v[190:193], v145 offset:53248
	ds_read_b128 v[194:197], v145 offset:54272
	ds_read_b128 v[198:201], v145 offset:55296
	ds_read_b128 v[202:205], v145 offset:56320
	global_load_lds_dwordx4 v[206:207], off
	s_add_i32 m0, s28, 0x2000
	s_add_u32 s26, s26, 0x40080
	v_lshl_add_u64 v[206:207], v[208:209], 0, s[18:19]
	s_addc_u32 s27, s27, 0
	s_add_i32 s28, s58, s33
	global_load_lds_dwordx4 v[206:207], off
	v_lshl_add_u64 v[206:207], s[26:27], 0, v[130:131]
	s_mov_b32 m0, s28
	s_nop 0
	global_load_lds_dwordx4 v[206:207], off
	v_lshl_add_u64 v[206:207], s[26:27], 0, v[128:129]
	s_add_i32 m0, s28, 0x2000
	s_nop 0
	global_load_lds_dwordx4 v[206:207], off
	v_lshl_add_u64 v[206:207], v[210:211], 0, s[18:19]
	s_mov_b32 m0, s39
	s_nop 0
	global_load_lds_dwordx4 v[206:207], off
	v_lshl_add_u64 v[206:207], v[212:213], 0, s[18:19]
	s_mov_b32 m0, s40
	s_nop 0
	global_load_lds_dwordx4 v[206:207], off
	s_waitcnt vmcnt(8)
	s_waitcnt lgkmcnt(0)
	s_barrier
	s_setprio 1
	s_waitcnt lgkmcnt(0)
	v_mfma_f32_16x16x32_bf16 v[60:63], v[136:139], v[174:177], v[60:63]
	v_mfma_f32_16x16x32_bf16 v[56:59], v[150:153], v[174:177], v[56:59]
	v_mfma_f32_16x16x32_bf16 v[44:47], v[136:139], v[182:185], v[44:47]
	v_mfma_f32_16x16x32_bf16 v[40:43], v[150:153], v[182:185], v[40:43]
	v_mfma_f32_16x16x32_bf16 v[28:31], v[136:139], v[190:193], v[28:31]
	v_mfma_f32_16x16x32_bf16 v[24:27], v[150:153], v[190:193], v[24:27]
	v_mfma_f32_16x16x32_bf16 v[12:15], v[136:139], v[198:201], v[12:15]
	v_mfma_f32_16x16x32_bf16 v[8:11], v[150:153], v[198:201], v[8:11]
	v_mfma_f32_16x16x32_bf16 v[60:63], v[146:149], v[178:181], v[60:63]
	v_mfma_f32_16x16x32_bf16 v[56:59], v[154:157], v[178:181], v[56:59]
	v_mfma_f32_16x16x32_bf16 v[44:47], v[146:149], v[186:189], v[44:47]
	v_mfma_f32_16x16x32_bf16 v[40:43], v[154:157], v[186:189], v[40:43]
	v_mfma_f32_16x16x32_bf16 v[28:31], v[146:149], v[194:197], v[28:31]
	v_mfma_f32_16x16x32_bf16 v[24:27], v[154:157], v[194:197], v[24:27]
	v_mfma_f32_16x16x32_bf16 v[12:15], v[146:149], v[202:205], v[12:15]
	v_mfma_f32_16x16x32_bf16 v[8:11], v[154:157], v[202:205], v[8:11]
	s_setprio 0
	s_setprio 1
	v_mfma_f32_16x16x32_bf16 v[52:55], v[158:161], v[174:177], v[52:55]
	v_mfma_f32_16x16x32_bf16 v[48:51], v[166:169], v[174:177], v[48:51]
	v_mfma_f32_16x16x32_bf16 v[36:39], v[158:161], v[182:185], v[36:39]
	v_mfma_f32_16x16x32_bf16 v[32:35], v[166:169], v[182:185], v[32:35]
	v_mfma_f32_16x16x32_bf16 v[20:23], v[158:161], v[190:193], v[20:23]
	v_mfma_f32_16x16x32_bf16 v[16:19], v[166:169], v[190:193], v[16:19]
	v_mfma_f32_16x16x32_bf16 v[4:7], v[158:161], v[198:201], v[4:7]
	v_mfma_f32_16x16x32_bf16 v[0:3], v[166:169], v[198:201], v[0:3]
	v_mfma_f32_16x16x32_bf16 v[52:55], v[162:165], v[178:181], v[52:55]
	v_mfma_f32_16x16x32_bf16 v[48:51], v[170:173], v[178:181], v[48:51]
	v_mfma_f32_16x16x32_bf16 v[36:39], v[162:165], v[186:189], v[36:39]
	v_mfma_f32_16x16x32_bf16 v[32:35], v[170:173], v[186:189], v[32:35]
	v_mfma_f32_16x16x32_bf16 v[20:23], v[162:165], v[194:197], v[20:23]
	v_mfma_f32_16x16x32_bf16 v[16:19], v[170:173], v[194:197], v[16:19]
	v_mfma_f32_16x16x32_bf16 v[4:7], v[162:165], v[202:205], v[4:7]
	v_mfma_f32_16x16x32_bf16 v[0:3], v[170:173], v[202:205], v[0:3]
	s_setprio 0
	s_barrier
	s_add_i32 s56, s56, 2
	s_add_u32 s24, s24, 0x100
	s_addc_u32 s25, s25, 0
	s_add_u32 s50, s50, 0x100
	s_addc_u32 s51, s51, 0
	s_cmp_gt_u32 s56, 13
	s_cbranch_scc0 .LBB0_1058
	s_and_b64 vcc, exec, s[20:21]
	s_cbranch_vccz .LBB0_1061
	s_barrier

.LBB0_1132:
	s_andn2_b64 vcc, exec, s[26:27]
	s_cbranch_vccnz .Lq5_entry
	ds_read_b128 v[148:151], v214
	ds_read_b128 v[152:155], v214 offset:1024
	ds_read_b128 v[156:159], v214 offset:2048
	ds_read_b128 v[160:163], v214 offset:3072
	ds_read_b128 v[132:135], v215
	ds_read_b128 v[136:139], v215 offset:1024
	ds_read_b128 v[140:143], v215 offset:2048
	ds_read_b128 v[144:147], v215 offset:3072
	v_lshl_add_u64 v[2:3], s[34:35], 0, v[200:201]
	s_add_i32 m0, s48, 0xc000
	s_waitcnt lgkmcnt(0)
	ds_read_b128 v[188:191], v216
	ds_read_b128 v[192:195], v216 offset:1024
	ds_read_b128 v[180:183], v216 offset:2048
	ds_read_b128 v[184:187], v216 offset:3072
	ds_read_b128 v[172:175], v216 offset:4096
	ds_read_b128 v[176:179], v216 offset:5120
	ds_read_b128 v[164:167], v216 offset:6144
	ds_read_b128 v[168:171], v216 offset:7168
	global_load_lds_dwordx4 v[2:3], off
	v_lshl_add_u64 v[2:3], s[34:35], 0, v[202:203]
	s_add_i32 m0, s48, 0xe000
	s_nop 0
	global_load_lds_dwordx4 v[2:3], off
	s_waitcnt vmcnt(8)
	s_waitcnt lgkmcnt(0)
	s_barrier
	s_setprio 1
	s_waitcnt lgkmcnt(0)
	s_nop 0
	v_mfma_f32_16x16x32_bf16 v[128:131], v[148:151], v[188:191], v[128:131]
	v_mfma_f32_16x16x32_bf16 v[124:127], v[156:159], v[188:191], v[124:127]
	v_mfma_f32_16x16x32_bf16 v[120:123], v[148:151], v[180:183], v[120:123]
	v_mfma_f32_16x16x32_bf16 v[116:119], v[156:159], v[180:183], v[116:119]
	v_mfma_f32_16x16x32_bf16 v[104:107], v[148:151], v[172:175], v[104:107]
	v_mfma_f32_16x16x32_bf16 v[100:103], v[156:159], v[172:175], v[100:103]
	v_mfma_f32_16x16x32_bf16 v[88:91], v[148:151], v[164:167], v[88:91]
	v_mfma_f32_16x16x32_bf16 v[84:87], v[156:159], v[164:167], v[84:87]
	v_mfma_f32_16x16x32_bf16 v[128:131], v[152:155], v[192:195], v[128:131]
	v_mfma_f32_16x16x32_bf16 v[124:127], v[160:163], v[192:195], v[124:127]
	v_mfma_f32_16x16x32_bf16 v[120:123], v[152:155], v[184:187], v[120:123]
	v_mfma_f32_16x16x32_bf16 v[116:119], v[160:163], v[184:187], v[116:119]
	v_mfma_f32_16x16x32_bf16 v[104:107], v[152:155], v[176:179], v[104:107]
	v_mfma_f32_16x16x32_bf16 v[100:103], v[160:163], v[176:179], v[100:103]
	v_mfma_f32_16x16x32_bf16 v[88:91], v[152:155], v[168:171], v[88:91]
	v_mfma_f32_16x16x32_bf16 v[84:87], v[160:163], v[168:171], v[84:87]
	s_setprio 0
	v_cmp_ne_u32_e64 s[2:3], 1, v217
	s_andn2_b64 vcc, exec, s[26:27]
	s_cbranch_vccnz .LBB0_1134
	s_setprio 1
	v_mfma_f32_16x16x32_bf16 v[112:115], v[132:135], v[188:191], v[112:115]
	v_mfma_f32_16x16x32_bf16 v[108:111], v[140:143], v[188:191], v[108:111]
	v_mfma_f32_16x16x32_bf16 v[96:99], v[132:135], v[180:183], v[96:99]
	v_mfma_f32_16x16x32_bf16 v[92:95], v[140:143], v[180:183], v[92:95]
	v_mfma_f32_16x16x32_bf16 v[80:83], v[132:135], v[172:175], v[80:83]
	v_mfma_f32_16x16x32_bf16 v[76:79], v[140:143], v[172:175], v[76:79]
	v_mfma_f32_16x16x32_bf16 v[72:75], v[132:135], v[164:167], v[72:75]
	v_mfma_f32_16x16x32_bf16 v[68:71], v[140:143], v[164:167], v[68:71]
	v_mfma_f32_16x16x32_bf16 v[112:115], v[136:139], v[192:195], v[112:115]
	v_mfma_f32_16x16x32_bf16 v[108:111], v[144:147], v[192:195], v[108:111]
	v_mfma_f32_16x16x32_bf16 v[96:99], v[136:139], v[184:187], v[96:99]
	v_mfma_f32_16x16x32_bf16 v[92:95], v[144:147], v[184:187], v[92:95]
	v_mfma_f32_16x16x32_bf16 v[80:83], v[136:139], v[176:179], v[80:83]
	v_mfma_f32_16x16x32_bf16 v[76:79], v[144:147], v[176:179], v[76:79]
	v_mfma_f32_16x16x32_bf16 v[72:75], v[136:139], v[168:171], v[72:75]
	v_mfma_f32_16x16x32_bf16 v[68:71], v[144:147], v[168:171], v[68:71]
	s_setprio 0

.LBB0_1138:
	s_barrier
	s_mov_b32 m0, s66
	v_lshl_add_u64 v[2:3], v[2:3], 0, s[16:17]
	s_add_u32 s56, s56, 0x80080
	ds_read_b128 v[188:191], v216 offset:49152
	ds_read_b128 v[192:195], v216 offset:50176
	ds_read_b128 v[180:183], v216 offset:51200
	ds_read_b128 v[184:187], v216 offset:52224
	ds_read_b128 v[172:175], v216 offset:53248
	ds_read_b128 v[176:179], v216 offset:54272
	ds_read_b128 v[164:167], v216 offset:55296
	ds_read_b128 v[168:171], v216 offset:56320
	global_load_lds_dwordx4 v[2:3], off
	v_lshl_add_u64 v[2:3], v[204:205], 0, s[16:17]
	s_mov_b32 m0, s67
	s_addc_u32 s57, s57, 0
	global_load_lds_dwordx4 v[2:3], off
	v_lshl_add_u64 v[2:3], s[56:57], 0, v[198:199]
	s_mov_b32 m0, s70
	s_and_b64 vcc, exec, s[2:3]
	global_load_lds_dwordx4 v[2:3], off
	v_lshl_add_u64 v[2:3], s[56:57], 0, v[196:197]
	s_mov_b32 m0, s71
	s_nop 0
	global_load_lds_dwordx4 v[2:3], off
	v_lshl_add_u64 v[2:3], v[206:207], 0, s[16:17]
	s_mov_b32 m0, s68
	s_nop 0
	global_load_lds_dwordx4 v[2:3], off
	v_lshl_add_u64 v[2:3], v[208:209], 0, s[16:17]
	s_mov_b32 m0, s69
	s_nop 0
	global_load_lds_dwordx4 v[2:3], off
	s_waitcnt vmcnt(8)
	s_waitcnt lgkmcnt(0)
	s_barrier
	s_cbranch_vccnz .LBB0_1131
	s_setprio 1
	s_waitcnt lgkmcnt(0)
	s_nop 0
	v_mfma_f32_16x16x32_bf16 v[64:67], v[148:151], v[188:191], v[64:67]
	v_mfma_f32_16x16x32_bf16 v[60:63], v[156:159], v[188:191], v[60:63]
	v_mfma_f32_16x16x32_bf16 v[48:51], v[148:151], v[180:183], v[48:51]
	v_mfma_f32_16x16x32_bf16 v[44:47], v[156:159], v[180:183], v[44:47]
	v_mfma_f32_16x16x32_bf16 v[32:35], v[148:151], v[172:175], v[32:35]
	v_mfma_f32_16x16x32_bf16 v[28:31], v[156:159], v[172:175], v[28:31]
	v_mfma_f32_16x16x32_bf16 v[16:19], v[148:151], v[164:167], v[16:19]
	v_mfma_f32_16x16x32_bf16 v[12:15], v[156:159], v[164:167], v[12:15]
	v_mfma_f32_16x16x32_bf16 v[64:67], v[152:155], v[192:195], v[64:67]
	v_mfma_f32_16x16x32_bf16 v[60:63], v[160:163], v[192:195], v[60:63]
	v_mfma_f32_16x16x32_bf16 v[48:51], v[152:155], v[184:187], v[48:51]
	v_mfma_f32_16x16x32_bf16 v[44:47], v[160:163], v[184:187], v[44:47]
	v_mfma_f32_16x16x32_bf16 v[32:35], v[152:155], v[176:179], v[32:35]
	v_mfma_f32_16x16x32_bf16 v[28:31], v[160:163], v[176:179], v[28:31]
	v_mfma_f32_16x16x32_bf16 v[16:19], v[152:155], v[168:171], v[16:19]
	v_mfma_f32_16x16x32_bf16 v[12:15], v[160:163], v[168:171], v[12:15]
	s_setprio 0
	s_setprio 1
	v_mfma_f32_16x16x32_bf16 v[56:59], v[132:135], v[188:191], v[56:59]
	v_mfma_f32_16x16x32_bf16 v[52:55], v[140:143], v[188:191], v[52:55]
	v_mfma_f32_16x16x32_bf16 v[40:43], v[132:135], v[180:183], v[40:43]
	v_mfma_f32_16x16x32_bf16 v[36:39], v[140:143], v[180:183], v[36:39]
	v_mfma_f32_16x16x32_bf16 v[24:27], v[132:135], v[172:175], v[24:27]
	v_mfma_f32_16x16x32_bf16 v[20:23], v[140:143], v[172:175], v[20:23]
	v_mfma_f32_16x16x32_bf16 v[8:11], v[132:135], v[164:167], v[8:11]
	v_mfma_f32_16x16x32_bf16 v[2:5], v[140:143], v[164:167], v[4:7]
	v_mfma_f32_16x16x32_bf16 v[56:59], v[136:139], v[192:195], v[56:59]
	v_mfma_f32_16x16x32_bf16 v[52:55], v[144:147], v[192:195], v[52:55]
	v_mfma_f32_16x16x32_bf16 v[40:43], v[136:139], v[184:187], v[40:43]
	v_mfma_f32_16x16x32_bf16 v[36:39], v[144:147], v[184:187], v[36:39]
	v_mfma_f32_16x16x32_bf16 v[24:27], v[136:139], v[176:179], v[24:27]
	v_mfma_f32_16x16x32_bf16 v[20:23], v[144:147], v[176:179], v[20:23]
	v_mfma_f32_16x16x32_bf16 v[8:11], v[136:139], v[168:171], v[8:11]
	v_mfma_f32_16x16x32_bf16 v[4:7], v[144:147], v[168:171], v[2:5]
	s_setprio 0
	s_branch .LBB0_1131

.Lq5_exit:
	s_nop 0
	v_mfma_f32_16x16x32_bf16 v[128:131], v[4:7], v[44:47], v[128:131]
	v_mfma_f32_16x16x32_bf16 v[124:127], v[12:15], v[44:47], v[124:127]
	v_mfma_f32_16x16x32_bf16 v[120:123], v[4:7], v[36:39], v[120:123]
	v_mfma_f32_16x16x32_bf16 v[116:119], v[12:15], v[36:39], v[116:119]
	v_mfma_f32_16x16x32_bf16 v[104:107], v[4:7], v[28:31], v[104:107]
	v_mfma_f32_16x16x32_bf16 v[100:103], v[12:15], v[28:31], v[100:103]
	v_mfma_f32_16x16x32_bf16 v[88:91], v[4:7], v[20:23], v[88:91]
	v_mfma_f32_16x16x32_bf16 v[84:87], v[12:15], v[20:23], v[84:87]
	v_mfma_f32_16x16x32_bf16 v[128:131], v[8:11], v[48:51], v[128:131]
	v_mfma_f32_16x16x32_bf16 v[124:127], v[16:19], v[48:51], v[124:127]
	v_mfma_f32_16x16x32_bf16 v[120:123], v[8:11], v[40:43], v[120:123]
	v_mfma_f32_16x16x32_bf16 v[116:119], v[16:19], v[40:43], v[116:119]
	v_mfma_f32_16x16x32_bf16 v[104:107], v[8:11], v[32:35], v[104:107]
	v_mfma_f32_16x16x32_bf16 v[100:103], v[16:19], v[32:35], v[100:103]
	v_mfma_f32_16x16x32_bf16 v[88:91], v[8:11], v[24:27], v[88:91]
	v_mfma_f32_16x16x32_bf16 v[84:87], v[16:19], v[24:27], v[84:87]
	s_nop 7
	s_nop 1
	s_branch .LBB0_1140

.LBB0_1283:
	s_andn2_b64 vcc, exec, s[34:35]
	s_cbranch_vccnz .Lq6_entry
	ds_read_b128 v[180:183], v247
	ds_read_b128 v[184:187], v247 offset:1024
	ds_read_b128 v[188:191], v247 offset:2048
	ds_read_b128 v[192:195], v247 offset:3072
	ds_read_b128 v[164:167], v248
	ds_read_b128 v[168:171], v248 offset:1024
	ds_read_b128 v[172:175], v248 offset:2048
	ds_read_b128 v[176:179], v248 offset:3072
	v_lshl_add_u64 v[2:3], s[38:39], 0, v[232:233]
	s_add_i32 m0, s44, 0xc000
	ds_read_b128 v[220:223], v249
	ds_read_b128 v[224:227], v249 offset:1024
	ds_read_b128 v[212:215], v249 offset:2048
	ds_read_b128 v[216:219], v249 offset:3072
	ds_read_b128 v[204:207], v249 offset:4096
	ds_read_b128 v[208:211], v249 offset:5120
	ds_read_b128 v[196:199], v249 offset:6144
	ds_read_b128 v[200:203], v249 offset:7168
	global_load_lds_dwordx4 v[2:3], off
	v_lshl_add_u64 v[2:3], s[38:39], 0, v[234:235]
	s_add_i32 m0, s44, 0xe000
	s_nop 0
	global_load_lds_dwordx4 v[2:3], off
	s_waitcnt vmcnt(8)
	s_waitcnt lgkmcnt(0)
	s_barrier
	s_setprio 1
	s_waitcnt lgkmcnt(0)
	s_nop 0
	v_mfma_f32_16x16x32_bf16 v[68:71], v[180:183], v[220:223], v[160:163]
	v_mfma_f32_16x16x32_bf16 v[72:75], v[188:191], v[220:223], v[156:159]
	v_mfma_f32_16x16x32_bf16 v[76:79], v[180:183], v[212:215], v[152:155]
	v_mfma_f32_16x16x32_bf16 v[80:83], v[188:191], v[212:215], v[148:151]
	v_mfma_f32_16x16x32_bf16 v[84:87], v[180:183], v[204:207], v[136:139]
	v_mfma_f32_16x16x32_bf16 v[92:95], v[188:191], v[204:207], v[132:135]
	v_mfma_f32_16x16x32_bf16 v[96:99], v[180:183], v[196:199], v[120:123]
	v_mfma_f32_16x16x32_bf16 v[100:103], v[188:191], v[196:199], v[112:115]
	v_mfma_f32_16x16x32_bf16 v[68:71], v[184:187], v[224:227], v[68:71]
	v_mfma_f32_16x16x32_bf16 v[72:75], v[192:195], v[224:227], v[72:75]
	v_mfma_f32_16x16x32_bf16 v[76:79], v[184:187], v[216:219], v[76:79]
	v_mfma_f32_16x16x32_bf16 v[80:83], v[192:195], v[216:219], v[80:83]
	v_mfma_f32_16x16x32_bf16 v[84:87], v[184:187], v[208:211], v[84:87]
	v_mfma_f32_16x16x32_bf16 v[92:95], v[192:195], v[208:211], v[92:95]
	v_mfma_f32_16x16x32_bf16 v[96:99], v[184:187], v[200:203], v[96:99]
	v_mfma_f32_16x16x32_bf16 v[100:103], v[192:195], v[200:203], v[100:103]
	s_setprio 0
	v_cmp_ne_u32_e64 s[4:5], 1, v251
	s_andn2_b64 vcc, exec, s[34:35]
	s_cbranch_vccnz .LBB0_1285
	s_setprio 1
	v_mfma_f32_16x16x32_bf16 v[112:115], v[164:167], v[220:223], v[144:147]
	v_mfma_f32_16x16x32_bf16 v[144:147], v[168:171], v[224:227], v[112:115]
	v_mfma_f32_16x16x32_bf16 v[112:115], v[172:175], v[220:223], v[140:143]
	v_mfma_f32_16x16x32_bf16 v[140:143], v[176:179], v[224:227], v[112:115]
	v_mfma_f32_16x16x32_bf16 v[112:115], v[164:167], v[212:215], v[128:131]
	v_mfma_f32_16x16x32_bf16 v[128:131], v[168:171], v[216:219], v[112:115]
	v_mfma_f32_16x16x32_bf16 v[112:115], v[172:175], v[212:215], v[124:127]
	v_mfma_f32_16x16x32_bf16 v[124:127], v[176:179], v[216:219], v[112:115]
	v_mfma_f32_16x16x32_bf16 v[112:115], v[164:167], v[204:207], v[116:119]
	v_mfma_f32_16x16x32_bf16 v[108:111], v[172:175], v[204:207], v[108:111]
	v_mfma_f32_16x16x32_bf16 v[104:107], v[164:167], v[196:199], v[104:107]
	v_mfma_f32_16x16x32_bf16 v[88:91], v[172:175], v[196:199], v[88:91]
	v_mfma_f32_16x16x32_bf16 v[116:119], v[168:171], v[208:211], v[112:115]
	v_mfma_f32_16x16x32_bf16 v[108:111], v[176:179], v[208:211], v[108:111]
	v_mfma_f32_16x16x32_bf16 v[104:107], v[168:171], v[200:203], v[104:107]
	v_mfma_f32_16x16x32_bf16 v[88:91], v[176:179], v[200:203], v[88:91]
	s_setprio 0
.LBB0_1285:
	s_add_u32 s40, s38, 0xfff80080
	s_addc_u32 s41, s39, -1
	s_cmp_eq_u32 s84, 28
	s_cselect_b32 s47, s29, s41
	s_cselect_b32 s46, s28, s40
	s_cselect_b32 s41, s37, s27
	s_cselect_b32 s40, s36, s16
	s_barrier
	s_mov_b32 m0, s45
	v_lshl_add_u64 v[2:3], s[40:41], 0, v[230:231]
	s_add_u32 s86, s40, 0x80000
	ds_read_b128 v[156:159], v249 offset:16384
	ds_read_b128 v[160:163], v249 offset:17408
	ds_read_b128 v[148:151], v249 offset:18432
	ds_read_b128 v[152:155], v249 offset:19456
	ds_read_b128 v[132:135], v249 offset:20480
	ds_read_b128 v[136:139], v249 offset:21504
	ds_read_b128 v[112:115], v249 offset:22528
	ds_read_b128 v[120:123], v249 offset:23552
	global_load_lds_dwordx4 v[2:3], off
	v_lshl_add_u64 v[236:237], s[40:41], 0, v[228:229]
	s_mov_b32 m0, s48
	s_addc_u32 s87, s41, 0
	global_load_lds_dwordx4 v[236:237], off
	v_lshl_add_u64 v[196:197], s[86:87], 0, v[230:231]
	s_mov_b32 m0, s49
	v_lshl_add_u64 v[238:239], s[46:47], 0, v[230:231]
	global_load_lds_dwordx4 v[196:197], off
	v_lshl_add_u64 v[196:197], s[86:87], 0, v[228:229]
	s_mov_b32 m0, s50
	v_lshl_add_u64 v[240:241], s[46:47], 0, v[228:229]
	global_load_lds_dwordx4 v[196:197], off
	s_mov_b32 m0, s44
	s_and_b64 vcc, exec, s[4:5]
	global_load_lds_dwordx4 v[238:239], off
	s_mov_b32 m0, s51
	s_nop 0
	global_load_lds_dwordx4 v[240:241], off
	s_waitcnt vmcnt(8)
	s_waitcnt lgkmcnt(0)
	s_barrier
	s_cbranch_vccnz .LBB0_1287
	s_setprio 1
	s_waitcnt lgkmcnt(0)
	s_nop 0
	v_mfma_f32_16x16x32_bf16 v[64:67], v[180:183], v[156:159], v[64:67]
	v_mfma_f32_16x16x32_bf16 v[60:63], v[188:191], v[156:159], v[60:63]
	v_mfma_f32_16x16x32_bf16 v[48:51], v[180:183], v[148:151], v[48:51]
	v_mfma_f32_16x16x32_bf16 v[44:47], v[188:191], v[148:151], v[44:47]
	v_mfma_f32_16x16x32_bf16 v[32:35], v[180:183], v[132:135], v[32:35]
	v_mfma_f32_16x16x32_bf16 v[28:31], v[188:191], v[132:135], v[28:31]
	v_mfma_f32_16x16x32_bf16 v[16:19], v[180:183], v[112:115], v[16:19]
	v_mfma_f32_16x16x32_bf16 v[12:15], v[188:191], v[112:115], v[12:15]
	v_mfma_f32_16x16x32_bf16 v[64:67], v[184:187], v[160:163], v[64:67]
	v_mfma_f32_16x16x32_bf16 v[60:63], v[192:195], v[160:163], v[60:63]
	v_mfma_f32_16x16x32_bf16 v[48:51], v[184:187], v[152:155], v[48:51]
	v_mfma_f32_16x16x32_bf16 v[44:47], v[192:195], v[152:155], v[44:47]
	v_mfma_f32_16x16x32_bf16 v[32:35], v[184:187], v[136:139], v[32:35]
	v_mfma_f32_16x16x32_bf16 v[28:31], v[192:195], v[136:139], v[28:31]
	v_mfma_f32_16x16x32_bf16 v[16:19], v[184:187], v[120:123], v[16:19]
	v_mfma_f32_16x16x32_bf16 v[12:15], v[192:195], v[120:123], v[12:15]
	s_setprio 0
	s_setprio 1
	v_mfma_f32_16x16x32_bf16 v[56:59], v[164:167], v[156:159], v[56:59]
	v_mfma_f32_16x16x32_bf16 v[52:55], v[172:175], v[156:159], v[52:55]
	v_mfma_f32_16x16x32_bf16 v[40:43], v[164:167], v[148:151], v[40:43]
	v_mfma_f32_16x16x32_bf16 v[36:39], v[172:175], v[148:151], v[36:39]
	v_mfma_f32_16x16x32_bf16 v[24:27], v[164:167], v[132:135], v[24:27]
	v_mfma_f32_16x16x32_bf16 v[20:23], v[172:175], v[132:135], v[20:23]
	v_mfma_f32_16x16x32_bf16 v[8:11], v[164:167], v[112:115], v[8:11]
	v_mfma_f32_16x16x32_bf16 v[4:7], v[172:175], v[112:115], v[4:7]
	v_mfma_f32_16x16x32_bf16 v[56:59], v[168:171], v[160:163], v[56:59]
	v_mfma_f32_16x16x32_bf16 v[52:55], v[176:179], v[160:163], v[52:55]
	v_mfma_f32_16x16x32_bf16 v[40:43], v[168:171], v[152:155], v[40:43]
	v_mfma_f32_16x16x32_bf16 v[36:39], v[176:179], v[152:155], v[36:39]
	v_mfma_f32_16x16x32_bf16 v[24:27], v[168:171], v[136:139], v[24:27]
	v_mfma_f32_16x16x32_bf16 v[20:23], v[176:179], v[136:139], v[20:23]
	v_mfma_f32_16x16x32_bf16 v[8:11], v[168:171], v[120:123], v[8:11]
	v_mfma_f32_16x16x32_bf16 v[4:7], v[176:179], v[120:123], v[4:7]
	s_setprio 0

.LBB0_1289:
	s_barrier
	s_mov_b32 m0, s61
	v_lshl_add_u64 v[2:3], v[2:3], 0, s[14:15]
	s_add_u32 s40, s40, 0x80080
	ds_read_b128 v[96:99], v249 offset:49152
	ds_read_b128 v[100:103], v249 offset:50176
	ds_read_b128 v[84:87], v249 offset:51200
	ds_read_b128 v[92:95], v249 offset:52224
	ds_read_b128 v[76:79], v249 offset:53248
	ds_read_b128 v[80:83], v249 offset:54272
	ds_read_b128 v[68:71], v249 offset:55296
	ds_read_b128 v[72:75], v249 offset:56320
	global_load_lds_dwordx4 v[2:3], off
	v_lshl_add_u64 v[2:3], v[236:237], 0, s[14:15]
	s_mov_b32 m0, s62
	s_addc_u32 s41, s41, 0
	global_load_lds_dwordx4 v[2:3], off
	v_lshl_add_u64 v[2:3], s[40:41], 0, v[230:231]
	s_mov_b32 m0, s65
	s_and_b64 vcc, exec, s[4:5]
	global_load_lds_dwordx4 v[2:3], off
	v_lshl_add_u64 v[2:3], s[40:41], 0, v[228:229]
	s_mov_b32 m0, s66
	s_nop 0
	global_load_lds_dwordx4 v[2:3], off
	v_lshl_add_u64 v[2:3], v[238:239], 0, s[14:15]
	s_mov_b32 m0, s63
	s_nop 0
	global_load_lds_dwordx4 v[2:3], off
	v_lshl_add_u64 v[2:3], v[240:241], 0, s[14:15]
	s_mov_b32 m0, s64
	s_nop 0
	global_load_lds_dwordx4 v[2:3], off
	s_waitcnt vmcnt(8)
	s_waitcnt lgkmcnt(0)
	s_barrier
	s_cbranch_vccnz .LBB0_1282
	s_setprio 1
	s_waitcnt lgkmcnt(0)
	s_nop 0
	v_mfma_f32_16x16x32_bf16 v[64:67], v[180:183], v[96:99], v[64:67]
	v_mfma_f32_16x16x32_bf16 v[60:63], v[188:191], v[96:99], v[60:63]
	v_mfma_f32_16x16x32_bf16 v[48:51], v[180:183], v[84:87], v[48:51]
	v_mfma_f32_16x16x32_bf16 v[44:47], v[188:191], v[84:87], v[44:47]
	v_mfma_f32_16x16x32_bf16 v[32:35], v[180:183], v[76:79], v[32:35]
	v_mfma_f32_16x16x32_bf16 v[28:31], v[188:191], v[76:79], v[28:31]
	v_mfma_f32_16x16x32_bf16 v[16:19], v[180:183], v[68:71], v[16:19]
	v_mfma_f32_16x16x32_bf16 v[12:15], v[188:191], v[68:71], v[12:15]
	v_mfma_f32_16x16x32_bf16 v[64:67], v[184:187], v[100:103], v[64:67]
	v_mfma_f32_16x16x32_bf16 v[60:63], v[192:195], v[100:103], v[60:63]
	v_mfma_f32_16x16x32_bf16 v[48:51], v[184:187], v[92:95], v[48:51]
	v_mfma_f32_16x16x32_bf16 v[44:47], v[192:195], v[92:95], v[44:47]
	v_mfma_f32_16x16x32_bf16 v[32:35], v[184:187], v[80:83], v[32:35]
	v_mfma_f32_16x16x32_bf16 v[28:31], v[192:195], v[80:83], v[28:31]
	v_mfma_f32_16x16x32_bf16 v[16:19], v[184:187], v[72:75], v[16:19]
	v_mfma_f32_16x16x32_bf16 v[12:15], v[192:195], v[72:75], v[12:15]
	s_setprio 0
	s_setprio 1
	v_mfma_f32_16x16x32_bf16 v[56:59], v[164:167], v[96:99], v[56:59]
	v_mfma_f32_16x16x32_bf16 v[52:55], v[172:175], v[96:99], v[52:55]
	v_mfma_f32_16x16x32_bf16 v[40:43], v[164:167], v[84:87], v[40:43]
	v_mfma_f32_16x16x32_bf16 v[36:39], v[172:175], v[84:87], v[36:39]
	v_mfma_f32_16x16x32_bf16 v[24:27], v[164:167], v[76:79], v[24:27]
	v_mfma_f32_16x16x32_bf16 v[20:23], v[172:175], v[76:79], v[20:23]
	v_mfma_f32_16x16x32_bf16 v[8:11], v[164:167], v[68:71], v[8:11]
	v_mfma_f32_16x16x32_bf16 v[2:5], v[172:175], v[68:71], v[4:7]
	v_mfma_f32_16x16x32_bf16 v[56:59], v[168:171], v[100:103], v[56:59]
	v_mfma_f32_16x16x32_bf16 v[52:55], v[176:179], v[100:103], v[52:55]
	v_mfma_f32_16x16x32_bf16 v[40:43], v[168:171], v[92:95], v[40:43]
	v_mfma_f32_16x16x32_bf16 v[36:39], v[176:179], v[92:95], v[36:39]
	v_mfma_f32_16x16x32_bf16 v[24:27], v[168:171], v[80:83], v[24:27]
	v_mfma_f32_16x16x32_bf16 v[20:23], v[176:179], v[80:83], v[20:23]
	v_mfma_f32_16x16x32_bf16 v[8:11], v[168:171], v[72:75], v[8:11]
	v_mfma_f32_16x16x32_bf16 v[4:7], v[176:179], v[72:75], v[2:5]
	s_setprio 0
	s_branch .LBB0_1282

.LBB0_1391:
	ds_read_b128 v[24:27], v234
	ds_read_b128 v[28:31], v234 offset:1024
	ds_read_b128 v[96:99], v234 offset:2048
	ds_read_b128 v[100:103], v234 offset:3072
	ds_read_b128 v[144:147], v235
	ds_read_b128 v[148:151], v235 offset:1024
	ds_read_b128 v[152:155], v235 offset:2048
	ds_read_b128 v[156:159], v235 offset:3072
	s_add_u32 s16, s14, 0xfff80080
	s_addc_u32 s17, s15, -1
	s_cmp_eq_u32 s22, 28
	s_cselect_b32 s19, s9, s17
	s_cselect_b32 s18, s13, s16
	s_cselect_b32 s17, s79, s21
	s_cselect_b32 s16, s78, s20
	v_lshl_add_u64 v[204:205], s[14:15], 0, v[192:193]
	s_add_i32 m0, s49, 0xc000
	ds_read_b128 v[160:163], v236
	ds_read_b128 v[164:167], v236 offset:1024
	ds_read_b128 v[168:171], v236 offset:2048
	ds_read_b128 v[172:175], v236 offset:3072
	ds_read_b128 v[176:179], v236 offset:4096
	ds_read_b128 v[180:183], v236 offset:5120
	ds_read_b128 v[196:199], v236 offset:6144
	ds_read_b128 v[200:203], v236 offset:7168
	global_load_lds_dwordx4 v[204:205], off
	v_lshl_add_u64 v[204:205], s[14:15], 0, v[194:195]
	s_add_i32 m0, s49, 0xe000
	s_nop 0
	global_load_lds_dwordx4 v[204:205], off
	s_waitcnt vmcnt(8)
	s_waitcnt lgkmcnt(0)
	s_barrier
	s_setprio 1
	s_waitcnt lgkmcnt(0)
	v_mfma_f32_16x16x32_bf16 v[140:143], v[24:27], v[160:163], v[140:143]
	v_mfma_f32_16x16x32_bf16 v[84:87], v[96:99], v[160:163], v[84:87]
	v_mfma_f32_16x16x32_bf16 v[116:119], v[24:27], v[168:171], v[116:119]
	v_mfma_f32_16x16x32_bf16 v[44:47], v[96:99], v[168:171], v[44:47]
	v_mfma_f32_16x16x32_bf16 v[108:111], v[24:27], v[176:179], v[108:111]
	v_mfma_f32_16x16x32_bf16 v[36:39], v[96:99], v[176:179], v[36:39]
	v_mfma_f32_16x16x32_bf16 v[136:139], v[24:27], v[196:199], v[136:139]
	v_mfma_f32_16x16x32_bf16 v[56:59], v[96:99], v[196:199], v[56:59]
	v_mfma_f32_16x16x32_bf16 v[140:143], v[28:31], v[164:167], v[140:143]
	v_mfma_f32_16x16x32_bf16 v[84:87], v[100:103], v[164:167], v[84:87]
	v_mfma_f32_16x16x32_bf16 v[116:119], v[28:31], v[172:175], v[116:119]
	v_mfma_f32_16x16x32_bf16 v[44:47], v[100:103], v[172:175], v[44:47]
	v_mfma_f32_16x16x32_bf16 v[108:111], v[28:31], v[180:183], v[108:111]
	v_mfma_f32_16x16x32_bf16 v[36:39], v[100:103], v[180:183], v[36:39]
	v_mfma_f32_16x16x32_bf16 v[136:139], v[28:31], v[200:203], v[136:139]
	v_mfma_f32_16x16x32_bf16 v[56:59], v[100:103], v[200:203], v[56:59]
	s_setprio 0
	s_setprio 1
	v_mfma_f32_16x16x32_bf16 v[128:131], v[144:147], v[160:163], v[128:131]
	v_mfma_f32_16x16x32_bf16 v[80:83], v[152:155], v[160:163], v[80:83]
	v_mfma_f32_16x16x32_bf16 v[112:115], v[144:147], v[168:171], v[112:115]
	v_mfma_f32_16x16x32_bf16 v[40:43], v[152:155], v[168:171], v[40:43]
	v_mfma_f32_16x16x32_bf16 v[104:107], v[144:147], v[176:179], v[104:107]
	v_mfma_f32_16x16x32_bf16 v[32:35], v[152:155], v[176:179], v[32:35]
	v_mfma_f32_16x16x32_bf16 v[132:135], v[144:147], v[196:199], v[132:135]
	v_mfma_f32_16x16x32_bf16 v[60:63], v[152:155], v[196:199], v[60:63]
	v_mfma_f32_16x16x32_bf16 v[128:131], v[148:151], v[164:167], v[128:131]
	v_mfma_f32_16x16x32_bf16 v[80:83], v[156:159], v[164:167], v[80:83]
	v_mfma_f32_16x16x32_bf16 v[112:115], v[148:151], v[172:175], v[112:115]
	v_mfma_f32_16x16x32_bf16 v[40:43], v[156:159], v[172:175], v[40:43]
	v_mfma_f32_16x16x32_bf16 v[104:107], v[148:151], v[180:183], v[104:107]
	v_mfma_f32_16x16x32_bf16 v[32:35], v[156:159], v[180:183], v[32:35]
	v_mfma_f32_16x16x32_bf16 v[132:135], v[148:151], v[200:203], v[132:135]
	v_mfma_f32_16x16x32_bf16 v[60:63], v[156:159], v[200:203], v[60:63]
	s_setprio 0
	s_barrier
	s_add_i32 s23, s45, s51
	v_lshl_add_u64 v[204:205], s[16:17], 0, v[188:189]
	s_mov_b32 m0, s23
	ds_read_b128 v[160:163], v236 offset:16384
	ds_read_b128 v[164:167], v236 offset:17408
	ds_read_b128 v[168:171], v236 offset:18432
	ds_read_b128 v[172:175], v236 offset:19456
	ds_read_b128 v[176:179], v236 offset:20480
	ds_read_b128 v[180:183], v236 offset:21504
	ds_read_b128 v[196:199], v236 offset:22528
	ds_read_b128 v[200:203], v236 offset:23552
	global_load_lds_dwordx4 v[204:205], off
	s_add_i32 m0, s23, 0x2000
	s_add_u32 s24, s16, 0x84000
	v_lshl_add_u64 v[206:207], s[16:17], 0, v[184:185]
	s_addc_u32 s25, s17, 0
	s_add_i32 s23, s48, s51
	global_load_lds_dwordx4 v[206:207], off
	v_lshl_add_u64 v[208:209], s[24:25], 0, v[188:189]
	s_mov_b32 m0, s23
	v_lshl_add_u64 v[210:211], s[18:19], 0, v[186:187]
	global_load_lds_dwordx4 v[208:209], off
	v_lshl_add_u64 v[208:209], s[24:25], 0, v[184:185]
	s_add_i32 m0, s23, 0x2000
	s_nop 0
	global_load_lds_dwordx4 v[208:209], off
	v_lshl_add_u64 v[208:209], s[18:19], 0, v[190:191]
	s_mov_b32 m0, s49
	s_nop 0
	global_load_lds_dwordx4 v[208:209], off
	s_mov_b32 m0, s50
	s_nop 0
	global_load_lds_dwordx4 v[210:211], off
	s_waitcnt vmcnt(8)
	s_waitcnt lgkmcnt(0)
	s_barrier
	s_setprio 1
	s_waitcnt lgkmcnt(0)
	s_nop 0
	v_mfma_f32_16x16x32_bf16 v[124:127], v[24:27], v[160:163], v[124:127]
	v_mfma_f32_16x16x32_bf16 v[52:55], v[96:99], v[160:163], v[52:55]
	v_mfma_f32_16x16x32_bf16 v[76:79], v[24:27], v[168:171], v[76:79]
	v_mfma_f32_16x16x32_bf16 v[12:15], v[96:99], v[168:171], v[12:15]
	v_mfma_f32_16x16x32_bf16 v[68:71], v[24:27], v[176:179], v[68:71]
	v_mfma_f32_16x16x32_bf16 v[4:7], v[96:99], v[176:179], v[4:7]
	v_mfma_f32_16x16x32_bf16 v[16:19], v[96:99], v[196:199], v[16:19]
	v_mfma_f32_16x16x32_bf16 v[124:127], v[28:31], v[164:167], v[124:127]
	v_mfma_f32_16x16x32_bf16 v[52:55], v[100:103], v[164:167], v[52:55]
	v_mfma_f32_16x16x32_bf16 v[76:79], v[28:31], v[172:175], v[76:79]
	v_mfma_f32_16x16x32_bf16 v[12:15], v[100:103], v[172:175], v[12:15]
	v_mfma_f32_16x16x32_bf16 v[68:71], v[28:31], v[180:183], v[68:71]
	v_mfma_f32_16x16x32_bf16 v[4:7], v[100:103], v[180:183], v[4:7]
	v_mfma_f32_16x16x32_bf16 v[24:27], v[24:27], v[196:199], v[88:91]
	v_mfma_f32_16x16x32_bf16 v[16:19], v[100:103], v[200:203], v[16:19]
	v_mfma_f32_16x16x32_bf16 v[24:27], v[28:31], v[200:203], v[24:27]
	s_setprio 0
	s_setprio 1
	v_mfma_f32_16x16x32_bf16 v[48:51], v[152:155], v[160:163], v[48:51]
	v_mfma_f32_16x16x32_bf16 v[72:75], v[144:147], v[168:171], v[72:75]
	v_mfma_f32_16x16x32_bf16 v[8:11], v[152:155], v[168:171], v[8:11]
	v_mfma_f32_16x16x32_bf16 v[64:67], v[144:147], v[176:179], v[64:67]
	v_mfma_f32_16x16x32_bf16 v[0:3], v[152:155], v[176:179], v[0:3]
	v_mfma_f32_16x16x32_bf16 v[88:91], v[144:147], v[196:199], v[92:95]
	v_mfma_f32_16x16x32_bf16 v[20:23], v[152:155], v[196:199], v[20:23]
	v_mfma_f32_16x16x32_bf16 v[28:31], v[144:147], v[160:163], v[120:123]
	v_mfma_f32_16x16x32_bf16 v[48:51], v[156:159], v[164:167], v[48:51]
	v_mfma_f32_16x16x32_bf16 v[72:75], v[148:151], v[172:175], v[72:75]
	v_mfma_f32_16x16x32_bf16 v[8:11], v[156:159], v[172:175], v[8:11]
	v_mfma_f32_16x16x32_bf16 v[64:67], v[148:151], v[180:183], v[64:67]
	v_mfma_f32_16x16x32_bf16 v[0:3], v[156:159], v[180:183], v[0:3]
	v_mfma_f32_16x16x32_bf16 v[92:95], v[148:151], v[200:203], v[88:91]
	v_mfma_f32_16x16x32_bf16 v[20:23], v[156:159], v[200:203], v[20:23]
	v_mfma_f32_16x16x32_bf16 v[28:31], v[148:151], v[164:167], v[28:31]
	s_setprio 0
	s_barrier
	s_add_i32 s23, 0, 0x18000
	s_add_i32 s24, 0, 0x1c000
	v_add_u32_e32 v120, s23, v222
	v_add_u32_e32 v156, s24, v222
	ds_read_b128 v[88:91], v120
	ds_read_b128 v[96:99], v120 offset:1024
	ds_read_b128 v[100:103], v120 offset:2048
	ds_read_b128 v[120:123], v120 offset:3072
	ds_read_b128 v[144:147], v156
	ds_read_b128 v[148:151], v156 offset:1024
	ds_read_b128 v[152:155], v156 offset:2048
	ds_read_b128 v[156:159], v156 offset:3072
	s_add_u32 s18, s18, 0x80000
	s_addc_u32 s19, s19, 0
	s_mov_b32 m0, s33
	v_lshl_add_u64 v[212:213], s[18:19], 0, v[190:191]
	ds_read_b128 v[160:163], v236 offset:32768
	ds_read_b128 v[164:167], v236 offset:33792
	ds_read_b128 v[168:171], v236 offset:34816
	ds_read_b128 v[172:175], v236 offset:35840
	ds_read_b128 v[176:179], v236 offset:36864
	ds_read_b128 v[180:183], v236 offset:37888
	ds_read_b128 v[196:199], v236 offset:38912
	ds_read_b128 v[200:203], v236 offset:39936
	global_load_lds_dwordx4 v[212:213], off
	v_lshl_add_u64 v[212:213], s[18:19], 0, v[186:187]
	s_mov_b32 m0, s30
	s_nop 0
	global_load_lds_dwordx4 v[212:213], off
	s_waitcnt vmcnt(8)
	s_waitcnt lgkmcnt(0)
	s_barrier
	s_setprio 1
	s_waitcnt lgkmcnt(0)
	s_nop 0
	v_mfma_f32_16x16x32_bf16 v[140:143], v[88:91], v[160:163], v[140:143]
	v_mfma_f32_16x16x32_bf16 v[84:87], v[100:103], v[160:163], v[84:87]
	v_mfma_f32_16x16x32_bf16 v[116:119], v[88:91], v[168:171], v[116:119]
	v_mfma_f32_16x16x32_bf16 v[44:47], v[100:103], v[168:171], v[44:47]
	v_mfma_f32_16x16x32_bf16 v[108:111], v[88:91], v[176:179], v[108:111]
	v_mfma_f32_16x16x32_bf16 v[36:39], v[100:103], v[176:179], v[36:39]
	v_mfma_f32_16x16x32_bf16 v[136:139], v[88:91], v[196:199], v[136:139]
	v_mfma_f32_16x16x32_bf16 v[56:59], v[100:103], v[196:199], v[56:59]
	v_mfma_f32_16x16x32_bf16 v[140:143], v[96:99], v[164:167], v[140:143]
	v_mfma_f32_16x16x32_bf16 v[84:87], v[120:123], v[164:167], v[84:87]
	v_mfma_f32_16x16x32_bf16 v[116:119], v[96:99], v[172:175], v[116:119]
	v_mfma_f32_16x16x32_bf16 v[44:47], v[120:123], v[172:175], v[44:47]
	v_mfma_f32_16x16x32_bf16 v[108:111], v[96:99], v[180:183], v[108:111]
	v_mfma_f32_16x16x32_bf16 v[36:39], v[120:123], v[180:183], v[36:39]
	v_mfma_f32_16x16x32_bf16 v[136:139], v[96:99], v[200:203], v[136:139]
	v_mfma_f32_16x16x32_bf16 v[56:59], v[120:123], v[200:203], v[56:59]
	s_setprio 0
	s_setprio 1
	v_mfma_f32_16x16x32_bf16 v[128:131], v[144:147], v[160:163], v[128:131]
	v_mfma_f32_16x16x32_bf16 v[80:83], v[152:155], v[160:163], v[80:83]
	v_mfma_f32_16x16x32_bf16 v[112:115], v[144:147], v[168:171], v[112:115]
	v_mfma_f32_16x16x32_bf16 v[40:43], v[152:155], v[168:171], v[40:43]
	v_mfma_f32_16x16x32_bf16 v[104:107], v[144:147], v[176:179], v[104:107]
	v_mfma_f32_16x16x32_bf16 v[32:35], v[152:155], v[176:179], v[32:35]
	v_mfma_f32_16x16x32_bf16 v[132:135], v[144:147], v[196:199], v[132:135]
	v_mfma_f32_16x16x32_bf16 v[60:63], v[152:155], v[196:199], v[60:63]
	v_mfma_f32_16x16x32_bf16 v[128:131], v[148:151], v[164:167], v[128:131]
	v_mfma_f32_16x16x32_bf16 v[80:83], v[156:159], v[164:167], v[80:83]
	v_mfma_f32_16x16x32_bf16 v[112:115], v[148:151], v[172:175], v[112:115]
	v_mfma_f32_16x16x32_bf16 v[40:43], v[156:159], v[172:175], v[40:43]
	v_mfma_f32_16x16x32_bf16 v[104:107], v[148:151], v[180:183], v[104:107]
	v_mfma_f32_16x16x32_bf16 v[32:35], v[156:159], v[180:183], v[32:35]
	v_mfma_f32_16x16x32_bf16 v[132:135], v[148:151], v[200:203], v[132:135]
	v_mfma_f32_16x16x32_bf16 v[60:63], v[156:159], v[200:203], v[60:63]
	s_setprio 0
	s_barrier
	s_add_i32 s18, s23, s51
	v_lshl_add_u64 v[204:205], v[204:205], 0, s[58:59]
	s_mov_b32 m0, s18
	ds_read_b128 v[160:163], v236 offset:49152
	ds_read_b128 v[164:167], v236 offset:50176
	ds_read_b128 v[168:171], v236 offset:51200
	ds_read_b128 v[172:175], v236 offset:52224
	ds_read_b128 v[176:179], v236 offset:53248
	ds_read_b128 v[180:183], v236 offset:54272
	ds_read_b128 v[196:199], v236 offset:55296
	ds_read_b128 v[200:203], v236 offset:56320
	global_load_lds_dwordx4 v[204:205], off
	s_add_i32 m0, s18, 0x2000
	s_add_u32 s16, s16, 0x84080
	v_lshl_add_u64 v[204:205], v[206:207], 0, s[58:59]
	s_addc_u32 s17, s17, 0
	s_add_i32 s18, s24, s51
	global_load_lds_dwordx4 v[204:205], off
	v_lshl_add_u64 v[204:205], s[16:17], 0, v[188:189]
	s_mov_b32 m0, s18
	s_nop 0
	global_load_lds_dwordx4 v[204:205], off
	v_lshl_add_u64 v[204:205], s[16:17], 0, v[184:185]
	s_add_i32 m0, s18, 0x2000
	s_nop 0
	global_load_lds_dwordx4 v[204:205], off
	v_lshl_add_u64 v[204:205], v[208:209], 0, s[58:59]
	s_mov_b32 m0, s31
	s_nop 0
	global_load_lds_dwordx4 v[204:205], off
	v_lshl_add_u64 v[204:205], v[210:211], 0, s[58:59]
	s_mov_b32 m0, s38
	s_nop 0
	global_load_lds_dwordx4 v[204:205], off
	s_waitcnt vmcnt(8)
	s_waitcnt lgkmcnt(0)
	s_barrier
	s_setprio 1
	s_waitcnt lgkmcnt(0)
	v_mfma_f32_16x16x32_bf16 v[124:127], v[88:91], v[160:163], v[124:127]
	v_mfma_f32_16x16x32_bf16 v[52:55], v[100:103], v[160:163], v[52:55]
	v_mfma_f32_16x16x32_bf16 v[76:79], v[88:91], v[168:171], v[76:79]
	v_mfma_f32_16x16x32_bf16 v[12:15], v[100:103], v[168:171], v[12:15]
	v_mfma_f32_16x16x32_bf16 v[68:71], v[88:91], v[176:179], v[68:71]
	v_mfma_f32_16x16x32_bf16 v[4:7], v[100:103], v[176:179], v[4:7]
	v_mfma_f32_16x16x32_bf16 v[24:27], v[88:91], v[196:199], v[24:27]
	v_mfma_f32_16x16x32_bf16 v[16:19], v[100:103], v[196:199], v[16:19]
	v_mfma_f32_16x16x32_bf16 v[124:127], v[96:99], v[164:167], v[124:127]
	v_mfma_f32_16x16x32_bf16 v[52:55], v[120:123], v[164:167], v[52:55]
	v_mfma_f32_16x16x32_bf16 v[76:79], v[96:99], v[172:175], v[76:79]
	v_mfma_f32_16x16x32_bf16 v[12:15], v[120:123], v[172:175], v[12:15]
	v_mfma_f32_16x16x32_bf16 v[68:71], v[96:99], v[180:183], v[68:71]
	v_mfma_f32_16x16x32_bf16 v[4:7], v[120:123], v[180:183], v[4:7]
	v_mfma_f32_16x16x32_bf16 v[88:91], v[96:99], v[200:203], v[24:27]
	v_mfma_f32_16x16x32_bf16 v[16:19], v[120:123], v[200:203], v[16:19]
	s_setprio 0
	s_setprio 1
	v_mfma_f32_16x16x32_bf16 v[24:27], v[144:147], v[160:163], v[28:31]
	v_mfma_f32_16x16x32_bf16 v[120:123], v[148:151], v[164:167], v[24:27]
	v_mfma_f32_16x16x32_bf16 v[24:27], v[152:155], v[160:163], v[48:51]
	v_mfma_f32_16x16x32_bf16 v[48:51], v[156:159], v[164:167], v[24:27]
	v_mfma_f32_16x16x32_bf16 v[24:27], v[144:147], v[168:171], v[72:75]
	v_mfma_f32_16x16x32_bf16 v[72:75], v[148:151], v[172:175], v[24:27]
	v_mfma_f32_16x16x32_bf16 v[24:27], v[144:147], v[176:179], v[64:67]
	v_mfma_f32_16x16x32_bf16 v[8:11], v[152:155], v[168:171], v[8:11]
	v_mfma_f32_16x16x32_bf16 v[64:67], v[148:151], v[180:183], v[24:27]
	v_mfma_f32_16x16x32_bf16 v[0:3], v[152:155], v[176:179], v[0:3]
	v_mfma_f32_16x16x32_bf16 v[24:27], v[144:147], v[196:199], v[92:95]
	v_mfma_f32_16x16x32_bf16 v[20:23], v[152:155], v[196:199], v[20:23]
	v_mfma_f32_16x16x32_bf16 v[8:11], v[156:159], v[172:175], v[8:11]
	v_mfma_f32_16x16x32_bf16 v[0:3], v[156:159], v[180:183], v[0:3]
	v_mfma_f32_16x16x32_bf16 v[92:95], v[148:151], v[200:203], v[24:27]
	v_mfma_f32_16x16x32_bf16 v[20:23], v[156:159], v[200:203], v[20:23]
	s_setprio 0
	s_barrier
	s_add_i32 s22, s22, 2
	s_add_u32 s14, s14, 0x100
	s_addc_u32 s15, s15, 0
	s_add_u32 s20, s20, 0x100
	s_addc_u32 s21, s21, 0
	s_cmp_gt_u32 s22, 29
	s_cbranch_scc0 .LBB0_1391
	s_and_b64 vcc, exec, s[82:83]
	s_cbranch_vccz .LBB0_1394
	s_barrier

.LBB0_1626:
	ds_read_b128 v[128:131], v224
	ds_read_b128 v[132:135], v224 offset:1024
	ds_read_b128 v[136:139], v224 offset:2048
	ds_read_b128 v[140:143], v224 offset:3072
	ds_read_b128 v[154:157], v225
	ds_read_b128 v[158:161], v225 offset:1024
	ds_read_b128 v[162:165], v225 offset:2048
	ds_read_b128 v[166:169], v225 offset:3072
	s_add_i32 s48, s34, 2
	s_add_u32 s35, s26, 0xffea0080
	s_addc_u32 s49, s27, -1
	s_cmp_eq_u32 s30, s34
	s_cselect_b32 s34, s54, s31
	s_cselect_b32 s61, s53, s49
	s_cselect_b32 s60, s52, s35
	s_cselect_b32 s35, s55, s33
	v_lshl_add_u64 v[202:203], s[26:27], 0, v[150:151]
	s_add_i32 m0, s66, 0xc000
	ds_read_b128 v[170:173], v226
	ds_read_b128 v[174:177], v226 offset:1024
	ds_read_b128 v[178:181], v226 offset:2048
	ds_read_b128 v[182:185], v226 offset:3072
	ds_read_b128 v[186:189], v226 offset:4096
	ds_read_b128 v[190:193], v226 offset:5120
	ds_read_b128 v[194:197], v226 offset:6144
	ds_read_b128 v[198:201], v226 offset:7168
	global_load_lds_dwordx4 v[202:203], off
	v_lshl_add_u64 v[202:203], s[26:27], 0, v[152:153]
	s_add_i32 m0, s66, 0xe000
	s_nop 0
	global_load_lds_dwordx4 v[202:203], off
	s_waitcnt vmcnt(8)
	s_waitcnt lgkmcnt(0)
	s_barrier
	s_setprio 1
	s_waitcnt lgkmcnt(0)
	s_nop 0
	v_mfma_f32_16x16x32_bf16 v[124:127], v[128:131], v[170:173], v[124:127]
	v_mfma_f32_16x16x32_bf16 v[120:123], v[136:139], v[170:173], v[120:123]
	v_mfma_f32_16x16x32_bf16 v[112:115], v[128:131], v[178:181], v[112:115]
	v_mfma_f32_16x16x32_bf16 v[104:107], v[136:139], v[178:181], v[104:107]
	v_mfma_f32_16x16x32_bf16 v[96:99], v[128:131], v[186:189], v[96:99]
	v_mfma_f32_16x16x32_bf16 v[88:91], v[136:139], v[186:189], v[88:91]
	v_mfma_f32_16x16x32_bf16 v[80:83], v[128:131], v[194:197], v[80:83]
	v_mfma_f32_16x16x32_bf16 v[72:75], v[136:139], v[194:197], v[72:75]
	v_mfma_f32_16x16x32_bf16 v[124:127], v[132:135], v[174:177], v[124:127]
	v_mfma_f32_16x16x32_bf16 v[120:123], v[140:143], v[174:177], v[120:123]
	v_mfma_f32_16x16x32_bf16 v[112:115], v[132:135], v[182:185], v[112:115]
	v_mfma_f32_16x16x32_bf16 v[104:107], v[140:143], v[182:185], v[104:107]
	v_mfma_f32_16x16x32_bf16 v[96:99], v[132:135], v[190:193], v[96:99]
	v_mfma_f32_16x16x32_bf16 v[88:91], v[140:143], v[190:193], v[88:91]
	v_mfma_f32_16x16x32_bf16 v[80:83], v[132:135], v[198:201], v[80:83]
	v_mfma_f32_16x16x32_bf16 v[72:75], v[140:143], v[198:201], v[72:75]
	s_setprio 0
	s_setprio 1
	v_mfma_f32_16x16x32_bf16 v[116:119], v[154:157], v[170:173], v[116:119]
	v_mfma_f32_16x16x32_bf16 v[108:111], v[162:165], v[170:173], v[108:111]
	v_mfma_f32_16x16x32_bf16 v[100:103], v[154:157], v[178:181], v[100:103]
	v_mfma_f32_16x16x32_bf16 v[92:95], v[162:165], v[178:181], v[92:95]
	v_mfma_f32_16x16x32_bf16 v[84:87], v[154:157], v[186:189], v[84:87]
	v_mfma_f32_16x16x32_bf16 v[76:79], v[162:165], v[186:189], v[76:79]
	v_mfma_f32_16x16x32_bf16 v[68:71], v[154:157], v[194:197], v[68:71]
	v_mfma_f32_16x16x32_bf16 v[64:67], v[162:165], v[194:197], v[64:67]
	v_mfma_f32_16x16x32_bf16 v[116:119], v[158:161], v[174:177], v[116:119]
	v_mfma_f32_16x16x32_bf16 v[108:111], v[166:169], v[174:177], v[108:111]
	v_mfma_f32_16x16x32_bf16 v[100:103], v[158:161], v[182:185], v[100:103]
	v_mfma_f32_16x16x32_bf16 v[92:95], v[166:169], v[182:185], v[92:95]
	v_mfma_f32_16x16x32_bf16 v[84:87], v[158:161], v[190:193], v[84:87]
	v_mfma_f32_16x16x32_bf16 v[76:79], v[166:169], v[190:193], v[76:79]
	v_mfma_f32_16x16x32_bf16 v[68:71], v[158:161], v[198:201], v[68:71]
	v_mfma_f32_16x16x32_bf16 v[64:67], v[166:169], v[198:201], v[64:67]
	s_setprio 0
	s_barrier
	s_add_i32 s49, s79, s65
	v_lshl_add_u64 v[202:203], s[34:35], 0, v[144:145]
	s_mov_b32 m0, s49
	ds_read_b128 v[170:173], v226 offset:16384
	ds_read_b128 v[174:177], v226 offset:17408
	ds_read_b128 v[178:181], v226 offset:18432
	ds_read_b128 v[182:185], v226 offset:19456
	ds_read_b128 v[186:189], v226 offset:20480
	ds_read_b128 v[190:193], v226 offset:21504
	ds_read_b128 v[194:197], v226 offset:22528
	ds_read_b128 v[198:201], v226 offset:23552
	global_load_lds_dwordx4 v[202:203], off
	s_add_i32 m0, s49, 0x2000
	s_add_u32 s50, s34, 0x160000
	v_lshl_add_u64 v[204:205], s[34:35], 0, v[146:147]
	s_addc_u32 s51, s35, 0
	s_add_i32 s49, s84, s65
	global_load_lds_dwordx4 v[204:205], off
	v_lshl_add_u64 v[206:207], s[50:51], 0, v[144:145]
	s_mov_b32 m0, s49
	v_lshl_add_u64 v[208:209], s[60:61], 0, v[146:147]
	global_load_lds_dwordx4 v[206:207], off
	v_lshl_add_u64 v[206:207], s[50:51], 0, v[146:147]
	s_add_i32 m0, s49, 0x2000
	s_nop 0
	global_load_lds_dwordx4 v[206:207], off
	v_lshl_add_u64 v[206:207], s[60:61], 0, v[144:145]
	s_mov_b32 m0, s66
	s_nop 0
	global_load_lds_dwordx4 v[206:207], off
	s_mov_b32 m0, s67
	s_nop 0
	global_load_lds_dwordx4 v[208:209], off
	s_waitcnt vmcnt(8)
	s_waitcnt lgkmcnt(0)
	s_barrier
	s_setprio 1
	s_waitcnt lgkmcnt(0)
	s_nop 0
	v_mfma_f32_16x16x32_bf16 v[60:63], v[128:131], v[170:173], v[60:63]
	v_mfma_f32_16x16x32_bf16 v[56:59], v[136:139], v[170:173], v[56:59]
	v_mfma_f32_16x16x32_bf16 v[48:51], v[128:131], v[178:181], v[48:51]
	v_mfma_f32_16x16x32_bf16 v[40:43], v[136:139], v[178:181], v[40:43]
	v_mfma_f32_16x16x32_bf16 v[32:35], v[128:131], v[186:189], v[32:35]
	v_mfma_f32_16x16x32_bf16 v[24:27], v[136:139], v[186:189], v[24:27]
	v_mfma_f32_16x16x32_bf16 v[16:19], v[128:131], v[194:197], v[16:19]
	v_mfma_f32_16x16x32_bf16 v[8:11], v[136:139], v[194:197], v[8:11]
	v_mfma_f32_16x16x32_bf16 v[60:63], v[132:135], v[174:177], v[60:63]
	v_mfma_f32_16x16x32_bf16 v[56:59], v[140:143], v[174:177], v[56:59]
	v_mfma_f32_16x16x32_bf16 v[48:51], v[132:135], v[182:185], v[48:51]
	v_mfma_f32_16x16x32_bf16 v[40:43], v[140:143], v[182:185], v[40:43]
	v_mfma_f32_16x16x32_bf16 v[32:35], v[132:135], v[190:193], v[32:35]
	v_mfma_f32_16x16x32_bf16 v[24:27], v[140:143], v[190:193], v[24:27]
	v_mfma_f32_16x16x32_bf16 v[16:19], v[132:135], v[198:201], v[16:19]
	v_mfma_f32_16x16x32_bf16 v[8:11], v[140:143], v[198:201], v[8:11]
	s_setprio 0
	s_setprio 1
	v_mfma_f32_16x16x32_bf16 v[52:55], v[154:157], v[170:173], v[52:55]
	v_mfma_f32_16x16x32_bf16 v[44:47], v[162:165], v[170:173], v[44:47]
	v_mfma_f32_16x16x32_bf16 v[36:39], v[154:157], v[178:181], v[36:39]
	v_mfma_f32_16x16x32_bf16 v[28:31], v[162:165], v[178:181], v[28:31]
	v_mfma_f32_16x16x32_bf16 v[20:23], v[154:157], v[186:189], v[20:23]
	v_mfma_f32_16x16x32_bf16 v[12:15], v[162:165], v[186:189], v[12:15]
	v_mfma_f32_16x16x32_bf16 v[4:7], v[154:157], v[194:197], v[4:7]
	v_mfma_f32_16x16x32_bf16 v[0:3], v[162:165], v[194:197], v[0:3]
	v_mfma_f32_16x16x32_bf16 v[52:55], v[158:161], v[174:177], v[52:55]
	v_mfma_f32_16x16x32_bf16 v[44:47], v[166:169], v[174:177], v[44:47]
	v_mfma_f32_16x16x32_bf16 v[36:39], v[158:161], v[182:185], v[36:39]
	v_mfma_f32_16x16x32_bf16 v[28:31], v[166:169], v[182:185], v[28:31]
	v_mfma_f32_16x16x32_bf16 v[20:23], v[158:161], v[190:193], v[20:23]
	v_mfma_f32_16x16x32_bf16 v[12:15], v[166:169], v[190:193], v[12:15]
	v_mfma_f32_16x16x32_bf16 v[4:7], v[158:161], v[198:201], v[4:7]
	v_mfma_f32_16x16x32_bf16 v[0:3], v[166:169], v[198:201], v[0:3]
	s_setprio 0
	s_barrier
	s_add_i32 s49, 0, 0x18000
	s_add_i32 s57, 0, 0x1c000
	v_add_u32_e32 v140, s49, v220
	v_add_u32_e32 v166, s57, v220
	ds_read_b128 v[128:131], v140
	ds_read_b128 v[132:135], v140 offset:1024
	ds_read_b128 v[136:139], v140 offset:2048
	ds_read_b128 v[140:143], v140 offset:3072
	ds_read_b128 v[154:157], v166
	ds_read_b128 v[158:161], v166 offset:1024
	ds_read_b128 v[162:165], v166 offset:2048
	ds_read_b128 v[166:169], v166 offset:3072
	s_add_u32 s50, s60, 0x160000
	s_addc_u32 s51, s61, 0
	s_mov_b32 m0, s68
	v_lshl_add_u64 v[210:211], s[50:51], 0, v[144:145]
	ds_read_b128 v[170:173], v226 offset:32768
	ds_read_b128 v[174:177], v226 offset:33792
	ds_read_b128 v[178:181], v226 offset:34816
	ds_read_b128 v[182:185], v226 offset:35840
	ds_read_b128 v[186:189], v226 offset:36864
	ds_read_b128 v[190:193], v226 offset:37888
	ds_read_b128 v[194:197], v226 offset:38912
	ds_read_b128 v[198:201], v226 offset:39936
	global_load_lds_dwordx4 v[210:211], off
	v_lshl_add_u64 v[210:211], s[50:51], 0, v[146:147]
	s_mov_b32 m0, s69
	s_nop 0
	global_load_lds_dwordx4 v[210:211], off
	s_waitcnt vmcnt(8)
	s_waitcnt lgkmcnt(0)
	s_barrier
	s_setprio 1
	s_waitcnt lgkmcnt(0)
	s_nop 0
	v_mfma_f32_16x16x32_bf16 v[124:127], v[128:131], v[170:173], v[124:127]
	v_mfma_f32_16x16x32_bf16 v[120:123], v[136:139], v[170:173], v[120:123]
	v_mfma_f32_16x16x32_bf16 v[112:115], v[128:131], v[178:181], v[112:115]
	v_mfma_f32_16x16x32_bf16 v[104:107], v[136:139], v[178:181], v[104:107]
	v_mfma_f32_16x16x32_bf16 v[96:99], v[128:131], v[186:189], v[96:99]
	v_mfma_f32_16x16x32_bf16 v[88:91], v[136:139], v[186:189], v[88:91]
	v_mfma_f32_16x16x32_bf16 v[80:83], v[128:131], v[194:197], v[80:83]
	v_mfma_f32_16x16x32_bf16 v[72:75], v[136:139], v[194:197], v[72:75]
	v_mfma_f32_16x16x32_bf16 v[124:127], v[132:135], v[174:177], v[124:127]
	v_mfma_f32_16x16x32_bf16 v[120:123], v[140:143], v[174:177], v[120:123]
	v_mfma_f32_16x16x32_bf16 v[112:115], v[132:135], v[182:185], v[112:115]
	v_mfma_f32_16x16x32_bf16 v[104:107], v[140:143], v[182:185], v[104:107]
	v_mfma_f32_16x16x32_bf16 v[96:99], v[132:135], v[190:193], v[96:99]
	v_mfma_f32_16x16x32_bf16 v[88:91], v[140:143], v[190:193], v[88:91]
	v_mfma_f32_16x16x32_bf16 v[80:83], v[132:135], v[198:201], v[80:83]
	v_mfma_f32_16x16x32_bf16 v[72:75], v[140:143], v[198:201], v[72:75]
	s_setprio 0
	s_setprio 1
	v_mfma_f32_16x16x32_bf16 v[116:119], v[154:157], v[170:173], v[116:119]
	v_mfma_f32_16x16x32_bf16 v[108:111], v[162:165], v[170:173], v[108:111]
	v_mfma_f32_16x16x32_bf16 v[100:103], v[154:157], v[178:181], v[100:103]
	v_mfma_f32_16x16x32_bf16 v[92:95], v[162:165], v[178:181], v[92:95]
	v_mfma_f32_16x16x32_bf16 v[84:87], v[154:157], v[186:189], v[84:87]
	v_mfma_f32_16x16x32_bf16 v[76:79], v[162:165], v[186:189], v[76:79]
	v_mfma_f32_16x16x32_bf16 v[68:71], v[154:157], v[194:197], v[68:71]
	v_mfma_f32_16x16x32_bf16 v[64:67], v[162:165], v[194:197], v[64:67]
	v_mfma_f32_16x16x32_bf16 v[116:119], v[158:161], v[174:177], v[116:119]
	v_mfma_f32_16x16x32_bf16 v[108:111], v[166:169], v[174:177], v[108:111]
	v_mfma_f32_16x16x32_bf16 v[100:103], v[158:161], v[182:185], v[100:103]
	v_mfma_f32_16x16x32_bf16 v[92:95], v[166:169], v[182:185], v[92:95]
	v_mfma_f32_16x16x32_bf16 v[84:87], v[158:161], v[190:193], v[84:87]
	v_mfma_f32_16x16x32_bf16 v[76:79], v[166:169], v[190:193], v[76:79]
	v_mfma_f32_16x16x32_bf16 v[68:71], v[158:161], v[198:201], v[68:71]
	v_mfma_f32_16x16x32_bf16 v[64:67], v[166:169], v[198:201], v[64:67]
	s_setprio 0
	s_barrier
	s_add_i32 s49, s49, s65
	v_lshl_add_u64 v[202:203], v[202:203], 0, s[24:25]
	s_mov_b32 m0, s49
	ds_read_b128 v[170:173], v226 offset:49152
	ds_read_b128 v[174:177], v226 offset:50176
	ds_read_b128 v[178:181], v226 offset:51200
	ds_read_b128 v[182:185], v226 offset:52224
	ds_read_b128 v[186:189], v226 offset:53248
	ds_read_b128 v[190:193], v226 offset:54272
	ds_read_b128 v[194:197], v226 offset:55296
	ds_read_b128 v[198:201], v226 offset:56320
	global_load_lds_dwordx4 v[202:203], off
	s_add_i32 m0, s49, 0x2000
	s_add_u32 s34, s34, 0x160080
	v_lshl_add_u64 v[202:203], v[204:205], 0, s[24:25]
	s_addc_u32 s35, s35, 0
	s_add_i32 s49, s57, s65
	global_load_lds_dwordx4 v[202:203], off
	v_lshl_add_u64 v[202:203], s[34:35], 0, v[144:145]
	s_mov_b32 m0, s49
	s_nop 0
	global_load_lds_dwordx4 v[202:203], off
	v_lshl_add_u64 v[202:203], s[34:35], 0, v[146:147]
	s_add_i32 m0, s49, 0x2000
	s_nop 0
	global_load_lds_dwordx4 v[202:203], off
	v_lshl_add_u64 v[202:203], v[206:207], 0, s[24:25]
	s_mov_b32 m0, s74
	s_nop 0
	global_load_lds_dwordx4 v[202:203], off
	v_lshl_add_u64 v[202:203], v[208:209], 0, s[24:25]
	s_mov_b32 m0, s75
	s_nop 0
	global_load_lds_dwordx4 v[202:203], off
	s_waitcnt vmcnt(8)
	s_waitcnt lgkmcnt(0)
	s_barrier
	s_setprio 1
	s_waitcnt lgkmcnt(0)
	v_mfma_f32_16x16x32_bf16 v[60:63], v[128:131], v[170:173], v[60:63]
	v_mfma_f32_16x16x32_bf16 v[56:59], v[136:139], v[170:173], v[56:59]
	v_mfma_f32_16x16x32_bf16 v[48:51], v[128:131], v[178:181], v[48:51]
	v_mfma_f32_16x16x32_bf16 v[40:43], v[136:139], v[178:181], v[40:43]
	v_mfma_f32_16x16x32_bf16 v[32:35], v[128:131], v[186:189], v[32:35]
	v_mfma_f32_16x16x32_bf16 v[24:27], v[136:139], v[186:189], v[24:27]
	v_mfma_f32_16x16x32_bf16 v[16:19], v[128:131], v[194:197], v[16:19]
	v_mfma_f32_16x16x32_bf16 v[8:11], v[136:139], v[194:197], v[8:11]
	v_mfma_f32_16x16x32_bf16 v[60:63], v[132:135], v[174:177], v[60:63]
	v_mfma_f32_16x16x32_bf16 v[56:59], v[140:143], v[174:177], v[56:59]
	v_mfma_f32_16x16x32_bf16 v[48:51], v[132:135], v[182:185], v[48:51]
	v_mfma_f32_16x16x32_bf16 v[40:43], v[140:143], v[182:185], v[40:43]
	v_mfma_f32_16x16x32_bf16 v[32:35], v[132:135], v[190:193], v[32:35]
	v_mfma_f32_16x16x32_bf16 v[24:27], v[140:143], v[190:193], v[24:27]
	v_mfma_f32_16x16x32_bf16 v[16:19], v[132:135], v[198:201], v[16:19]
	v_mfma_f32_16x16x32_bf16 v[8:11], v[140:143], v[198:201], v[8:11]
	s_setprio 0
	s_setprio 1
	v_mfma_f32_16x16x32_bf16 v[52:55], v[154:157], v[170:173], v[52:55]
	v_mfma_f32_16x16x32_bf16 v[44:47], v[162:165], v[170:173], v[44:47]
	v_mfma_f32_16x16x32_bf16 v[36:39], v[154:157], v[178:181], v[36:39]
	v_mfma_f32_16x16x32_bf16 v[28:31], v[162:165], v[178:181], v[28:31]
	v_mfma_f32_16x16x32_bf16 v[20:23], v[154:157], v[186:189], v[20:23]
	v_mfma_f32_16x16x32_bf16 v[12:15], v[162:165], v[186:189], v[12:15]
	v_mfma_f32_16x16x32_bf16 v[4:7], v[154:157], v[194:197], v[4:7]
	v_mfma_f32_16x16x32_bf16 v[0:3], v[162:165], v[194:197], v[0:3]
	v_mfma_f32_16x16x32_bf16 v[52:55], v[158:161], v[174:177], v[52:55]
	v_mfma_f32_16x16x32_bf16 v[44:47], v[166:169], v[174:177], v[44:47]
	v_mfma_f32_16x16x32_bf16 v[36:39], v[158:161], v[182:185], v[36:39]
	v_mfma_f32_16x16x32_bf16 v[28:31], v[166:169], v[182:185], v[28:31]
	v_mfma_f32_16x16x32_bf16 v[20:23], v[158:161], v[190:193], v[20:23]
	v_mfma_f32_16x16x32_bf16 v[12:15], v[166:169], v[190:193], v[12:15]
	v_mfma_f32_16x16x32_bf16 v[4:7], v[158:161], v[198:201], v[4:7]
	v_mfma_f32_16x16x32_bf16 v[0:3], v[166:169], v[198:201], v[0:3]
	s_setprio 0
	s_barrier
	s_add_u32 s26, s26, 0x100
	s_addc_u32 s27, s27, 0
	s_add_u32 s31, s31, 0x100
	s_addc_u32 s33, s33, 0
	s_cmp_ge_u32 s48, s16
	s_mov_b32 s34, s48
	s_cbranch_scc0 .LBB0_1626
	s_and_b64 vcc, exec, s[28:29]
	s_cbranch_vccz .LBB0_1629
	s_barrier
